# v19 + removed redundant hand-written lgkmcnt(0) inside qk_tile (hipcc's counted waits already guard each MFMA) + permlane32_swap tile_max
# speedup vs baseline: 1.0035x; 1.0035x over previous
; DI unsigned cvtpk(float lo, float hi) { f32x2_t v = {lo, hi}; bf16x2_t b = __builtin_convertvector(v, bf16x2_t); return __builtin_bit_cast(unsigned, b); }
; DI void qk_tile(const char* kb, const bf16x8 (&qr)[5], int r32, int hi, f32x16& x0, f32x16& x1) {
;     bf16x8 kf[10];
; #pragma unroll
;     for (int d0 = 0; d0 < 4; ++d0) {
;         kf[2 * d0] = *(const bf16x8*)(kb + (2 * d0 + hi) * 1024 + r32 * 16);
;         kf[2 * d0 + 1] = *(const bf16x8*)(kb + (2 * d0 + hi) * 1024 + 512 + r32 * 16);
;     }
;     kf[8] = *(const bf16x8*)(kb + 8192 + r32 * 16);
;     kf[9] = *(const bf16x8*)(kb + 8192 + 512 + r32 * 16);
;     asm volatile("s_waitcnt lgkmcnt(0)" ::: "memory");
; #pragma unroll
;     for (int i = 0; i < 16; ++i) { x0[i] = 0.f; x1[i] = 0.f; }
; #pragma unroll
;     for (int d0 = 0; d0 < 5; ++d0) { x0 = MFMA32(kf[2 * d0], qr[d0], x0); x1 = MFMA32(kf[2 * d0 + 1], qr[d0], x1); }
; }
; DI void v_load(const char* vb, int lane, int hi, bf16x8 (&vf)[8]) {
;     const lds_cptr vp = (lds_cptr)vb + ((lane >> 4) & 1) * 32 + (lane & 3) * 8 + (4 * hi + ((lane & 15) >> 2)) * 64;
; #pragma unroll
;     for (int ks = 0; ks < 4; ++ks) {
;         { const s16x4 lo = vtr(vp + ks * 1024), hh = vtr(vp + ks * 1024 + 512); vf[ks] = (bf16x8){lo[0], lo[1], lo[2], lo[3], hh[0], hh[1], hh[2], hh[3]}; }
;         { const s16x4 lo = vtr(vp + 4096 + ks * 1024), hh = vtr(vp + 4096 + ks * 1024 + 512); vf[4 + ks] = (bf16x8){lo[0], lo[1], lo[2], lo[3], hh[0], hh[1], hh[2], hh[3]}; }
;     }
;     asm volatile("" ::: "memory");
; }
; DI void pv_tile(const bf16x8 (&vf)[8], const f32x16& p0, const f32x16& p1, f32x16& o0, f32x16& o1) {
;     u32x4 w[4];
; #pragma unroll
;     for (int j = 0; j < 4; ++j) { w[0][j] = cvtpk(p0[2 * j], p0[2 * j + 1]); w[1][j] = cvtpk(p0[8 + 2 * j], p0[9 + 2 * j]);
;                                   w[2][j] = cvtpk(p1[2 * j], p1[2 * j + 1]); w[3][j] = cvtpk(p1[8 + 2 * j], p1[9 + 2 * j]); }
; #pragma unroll
;     for (int ks = 0; ks < 4; ++ks) { const bf16x8 pb = __builtin_bit_cast(bf16x8, w[ks]); o0 = MFMA32(vf[ks], pb, o0); o1 = MFMA32(vf[4 + ks], pb, o1); }
; }
; DI void mask_tile(f32x16& x0, f32x16& x1, int klo, int khi, int hi) {
; #pragma unroll
;     for (int i = 0; i < 16; ++i) { const int k = crow(i, hi); if (k < klo || k > khi) x0[i] = NEGX; if (k + 32 < klo || k + 32 > khi) x1[i] = NEGX; }
.LBB0_326:
	v_cmp_le_f32_e32 vcc, s58, v159
	s_cbranch_vccz .LBB0_330
	s_mul_i32 s16, s26, 0x4800
	s_add_i32 s16, s16, 0
	v_add_u32_e32 v0, s16, v167
	v_add_u32_e32 v14, v0, v168
	ds_read_b128 v[2:5], v14
	ds_read_b128 v[6:9], v14 offset:512
	ds_read_b128 v[10:13], v14 offset:2048
	ds_read_b128 v[124:127], v14 offset:2560
	ds_read_b128 v[128:131], v14 offset:4096
	ds_read_b128 v[132:135], v14 offset:4608
	ds_read_b128 v[136:139], v14 offset:6144
	ds_read_b128 v[140:143], v14 offset:6656
	ds_read_b128 v[220:223], v0 offset:8192
	ds_read_b128 v[224:227], v0 offset:8704
	s_waitcnt lgkmcnt(9)
	v_mfma_f32_32x32x16_bf16 v[64:79], v[2:5], v[96:99], 0
	s_mov_b32 s81, s80
	s_mov_b32 s82, s80
	s_mov_b32 s83, s80
	v_mov_b64_e32 v[2:3], s[80:81]
	v_add3_u32 v0, s16, v169, v165
	v_mov_b64_e32 v[4:5], s[82:83]
	s_waitcnt lgkmcnt(8)
	v_mfma_f32_32x32x16_bf16 v[48:63], v[6:9], v[96:99], 0
	v_add3_u32 v0, v0, v170, v171
	s_cmp_lt_i32 s22, s13
	s_waitcnt lgkmcnt(7)
	v_mfma_f32_32x32x16_bf16 v[64:79], v[10:13], v[100:103], v[64:79]
	s_waitcnt lgkmcnt(6)
	v_mfma_f32_32x32x16_bf16 v[48:63], v[124:127], v[100:103], v[48:63]
	s_waitcnt lgkmcnt(5)
	v_mfma_f32_32x32x16_bf16 v[64:79], v[128:131], v[104:107], v[64:79]
	s_waitcnt lgkmcnt(4)
	v_mfma_f32_32x32x16_bf16 v[48:63], v[132:135], v[104:107], v[48:63]
	s_waitcnt lgkmcnt(3)
	v_mfma_f32_32x32x16_bf16 v[64:79], v[136:139], v[108:111], v[64:79]
	s_waitcnt lgkmcnt(2)
	v_mfma_f32_32x32x16_bf16 v[48:63], v[140:143], v[108:111], v[48:63]
	s_waitcnt lgkmcnt(1)
	v_mfma_f32_32x32x16_bf16 v[64:79], v[220:223], v[2:5], v[64:79]
	s_waitcnt lgkmcnt(0)
	v_mfma_f32_32x32x16_bf16 v[48:63], v[224:227], v[2:5], v[48:63]
	ds_read_b64_tr_b16 v[140:141], v0 offset:9216
	ds_read_b64_tr_b16 v[142:143], v0 offset:9728
	ds_read_b64_tr_b16 v[136:137], v0 offset:13312
	ds_read_b64_tr_b16 v[138:139], v0 offset:13824
	ds_read_b64_tr_b16 v[132:133], v0 offset:10240
	ds_read_b64_tr_b16 v[134:135], v0 offset:10752
	ds_read_b64_tr_b16 v[128:129], v0 offset:14336
	ds_read_b64_tr_b16 v[130:131], v0 offset:14848
	ds_read_b64_tr_b16 v[124:125], v0 offset:11264
	ds_read_b64_tr_b16 v[126:127], v0 offset:11776
	ds_read_b64_tr_b16 v[10:11], v0 offset:15360
	ds_read_b64_tr_b16 v[12:13], v0 offset:15872
	ds_read_b64_tr_b16 v[2:3], v0 offset:12288
	ds_read_b64_tr_b16 v[4:5], v0 offset:12800
	ds_read_b64_tr_b16 v[6:7], v0 offset:16384
	ds_read_b64_tr_b16 v[8:9], v0 offset:16896
	s_cbranch_scc1 .LBB0_329
	v_cmp_le_i32_e32 vcc, v188, v218
	s_nop 1
	v_cndmask_b32_e32 v48, v180, v48, vcc
	v_cmp_lt_i32_e32 vcc, v187, v218
	s_nop 1
	v_cndmask_b32_e32 v65, v180, v65, vcc
	v_cmp_le_i32_e32 vcc, v187, v218
	s_nop 1
	v_cndmask_b32_e32 v64, v180, v64, vcc
	v_cmp_le_i32_e32 vcc, v189, v218
	s_nop 1
	v_cndmask_b32_e32 v49, v180, v49, vcc
	v_cmp_le_i32_e32 vcc, v190, v218
	s_nop 1
	v_cndmask_b32_e32 v66, v180, v66, vcc
	v_cmp_le_i32_e32 vcc, v191, v218
	s_nop 1
	v_cndmask_b32_e32 v50, v180, v50, vcc
	v_cmp_le_i32_e32 vcc, v192, v218
	s_nop 1
	v_cndmask_b32_e32 v67, v180, v67, vcc
	v_cmp_le_i32_e32 vcc, v193, v218
	s_nop 1
	v_cndmask_b32_e32 v51, v180, v51, vcc
	v_cmp_le_i32_e32 vcc, v194, v218
	s_nop 1
	v_cndmask_b32_e32 v68, v180, v68, vcc
	v_cmp_le_i32_e32 vcc, v195, v218
	s_nop 1
	v_cndmask_b32_e32 v52, v180, v52, vcc
	v_cmp_le_i32_e32 vcc, v196, v218
	s_nop 1
	v_cndmask_b32_e32 v69, v180, v69, vcc
	v_cmp_le_i32_e32 vcc, v197, v218
	s_nop 1
	v_cndmask_b32_e32 v53, v180, v53, vcc
	v_cmp_le_i32_e32 vcc, v198, v218
	s_nop 1
	v_cndmask_b32_e32 v70, v180, v70, vcc
	v_cmp_le_i32_e32 vcc, v199, v218
	s_nop 1
	v_cndmask_b32_e32 v54, v180, v54, vcc
	v_cmp_le_i32_e32 vcc, v200, v218
	s_nop 1
	v_cndmask_b32_e32 v71, v180, v71, vcc
	v_cmp_le_i32_e32 vcc, v201, v218
	s_nop 1
	v_cndmask_b32_e32 v55, v180, v55, vcc
	v_cmp_le_i32_e32 vcc, v202, v218
	s_nop 1
	v_cndmask_b32_e32 v72, v180, v72, vcc
	v_cmp_le_i32_e32 vcc, v203, v218
	s_nop 1
	v_cndmask_b32_e32 v56, v180, v56, vcc
	v_cmp_le_i32_e32 vcc, v204, v218
	s_nop 1
	v_cndmask_b32_e32 v73, v180, v73, vcc
	v_cmp_le_i32_e32 vcc, v205, v218
	s_nop 1
	v_cndmask_b32_e32 v57, v180, v57, vcc
	v_cmp_le_i32_e32 vcc, v206, v218
	s_nop 1
	v_cndmask_b32_e32 v74, v180, v74, vcc
	v_cmp_le_i32_e32 vcc, v207, v218
	s_nop 1
	v_cndmask_b32_e32 v58, v180, v58, vcc
	v_cmp_le_i32_e32 vcc, v208, v218
	s_nop 1
	v_cndmask_b32_e32 v75, v180, v75, vcc
	v_cmp_le_i32_e32 vcc, v209, v218
	s_nop 1
	v_cndmask_b32_e32 v59, v180, v59, vcc
	v_cmp_le_i32_e32 vcc, v210, v218
	s_nop 1
	v_cndmask_b32_e32 v76, v180, v76, vcc
	v_cmp_le_i32_e32 vcc, v211, v218
	s_nop 1
	v_cndmask_b32_e32 v60, v180, v60, vcc
	v_cmp_le_i32_e32 vcc, v212, v218
	s_nop 1
	v_cndmask_b32_e32 v77, v180, v77, vcc
	v_cmp_le_i32_e32 vcc, v213, v218
	s_nop 1
	v_cndmask_b32_e32 v61, v180, v61, vcc
	v_cmp_le_i32_e32 vcc, v214, v218
	s_nop 1
	v_cndmask_b32_e32 v78, v180, v78, vcc
	v_cmp_le_i32_e32 vcc, v215, v218
	s_nop 1
	v_cndmask_b32_e32 v62, v180, v62, vcc
	v_cmp_le_i32_e32 vcc, v216, v218
	s_nop 1
	v_cndmask_b32_e32 v79, v180, v79, vcc
	v_cmp_le_i32_e32 vcc, v217, v218
	s_nop 1
	v_cndmask_b32_e32 v63, v180, v63, vcc

; DI unsigned cvtpk(float lo, float hi) { f32x2_t v = {lo, hi}; bf16x2_t b = __builtin_convertvector(v, bf16x2_t); return __builtin_bit_cast(unsigned, b); }
; DI void qk_tile(const char* kb, const bf16x8 (&qr)[5], int r32, int hi, f32x16& x0, f32x16& x1) {
;     bf16x8 kf[10];
; #pragma unroll
;     for (int d0 = 0; d0 < 4; ++d0) {
;         kf[2 * d0] = *(const bf16x8*)(kb + (2 * d0 + hi) * 1024 + r32 * 16);
;         kf[2 * d0 + 1] = *(const bf16x8*)(kb + (2 * d0 + hi) * 1024 + 512 + r32 * 16);
;     }
;     kf[8] = *(const bf16x8*)(kb + 8192 + r32 * 16);
;     kf[9] = *(const bf16x8*)(kb + 8192 + 512 + r32 * 16);
;     asm volatile("s_waitcnt lgkmcnt(0)" ::: "memory");
; #pragma unroll
;     for (int i = 0; i < 16; ++i) { x0[i] = 0.f; x1[i] = 0.f; }
; #pragma unroll
;     for (int d0 = 0; d0 < 5; ++d0) { x0 = MFMA32(kf[2 * d0], qr[d0], x0); x1 = MFMA32(kf[2 * d0 + 1], qr[d0], x1); }
; }
; DI void v_load(const char* vb, int lane, int hi, bf16x8 (&vf)[8]) {
;     const lds_cptr vp = (lds_cptr)vb + ((lane >> 4) & 1) * 32 + (lane & 3) * 8 + (4 * hi + ((lane & 15) >> 2)) * 64;
; #pragma unroll
;     for (int ks = 0; ks < 4; ++ks) {
;         { const s16x4 lo = vtr(vp + ks * 1024), hh = vtr(vp + ks * 1024 + 512); vf[ks] = (bf16x8){lo[0], lo[1], lo[2], lo[3], hh[0], hh[1], hh[2], hh[3]}; }
;         { const s16x4 lo = vtr(vp + 4096 + ks * 1024), hh = vtr(vp + 4096 + ks * 1024 + 512); vf[4 + ks] = (bf16x8){lo[0], lo[1], lo[2], lo[3], hh[0], hh[1], hh[2], hh[3]}; }
;     }
;     asm volatile("" ::: "memory");
; }
; DI void pv_tile(const bf16x8 (&vf)[8], const f32x16& p0, const f32x16& p1, f32x16& o0, f32x16& o1) {
;     u32x4 w[4];
; #pragma unroll
;     for (int j = 0; j < 4; ++j) { w[0][j] = cvtpk(p0[2 * j], p0[2 * j + 1]); w[1][j] = cvtpk(p0[8 + 2 * j], p0[9 + 2 * j]);
;                                   w[2][j] = cvtpk(p1[2 * j], p1[2 * j + 1]); w[3][j] = cvtpk(p1[8 + 2 * j], p1[9 + 2 * j]); }
; #pragma unroll
;     for (int ks = 0; ks < 4; ++ks) { const bf16x8 pb = __builtin_bit_cast(bf16x8, w[ks]); o0 = MFMA32(vf[ks], pb, o0); o1 = MFMA32(vf[4 + ks], pb, o1); }
; }
; DI void mask_tile(f32x16& x0, f32x16& x1, int klo, int khi, int hi) {
; #pragma unroll
;     for (int i = 0; i < 16; ++i) { const int k = crow(i, hi); if (k < klo || k > khi) x0[i] = NEGX; if (k + 32 < klo || k + 32 > khi) x1[i] = NEGX; }
.LBB0_351:
	s_andn2_b64 vcc, exec, s[22:23]
	s_cbranch_vccnz .LBB0_357
	s_mulk_i32 s19, 0x4800
	s_add_i32 s19, s19, 0
	v_add_u32_e32 v0, s19, v197
	v_add_u32_e32 v85, v0, v198
	ds_read_b128 v[34:37], v85
	s_waitcnt vmcnt(4)
	ds_read_b128 v[38:41], v85 offset:512
	ds_read_b128 v[114:117], v85 offset:2048
	ds_read_b128 v[118:121], v85 offset:2560
	s_add_i32 s22, s18, 0x7f
	s_cmp_le_i32 s22, s28
	s_waitcnt lgkmcnt(3)
	v_mfma_f32_32x32x16_bf16 v[50:65], v[34:37], v[66:69], 0
	s_waitcnt vmcnt(2) lgkmcnt(2)
	v_mfma_f32_32x32x16_bf16 v[34:49], v[38:41], v[66:69], 0
	s_waitcnt lgkmcnt(1)
	v_mfma_f32_32x32x16_bf16 v[50:65], v[114:117], v[70:73], v[50:65]
	s_waitcnt lgkmcnt(0)
	v_mfma_f32_32x32x16_bf16 v[34:49], v[118:121], v[70:73], v[34:49]
	ds_read_b128 v[114:117], v85 offset:4096
	ds_read_b128 v[118:121], v85 offset:4608
	s_waitcnt lgkmcnt(1)
	v_mfma_f32_32x32x16_bf16 v[50:65], v[114:117], v[74:77], v[50:65]
	s_waitcnt lgkmcnt(0)
	v_mfma_f32_32x32x16_bf16 v[34:49], v[118:121], v[74:77], v[34:49]
	ds_read_b128 v[114:117], v85 offset:6144
	ds_read_b128 v[118:121], v85 offset:6656
	s_waitcnt lgkmcnt(1)
	v_mfma_f32_32x32x16_bf16 v[50:65], v[114:117], v[78:81], v[50:65]
	ds_read_b128 v[114:117], v0 offset:8192
	ds_read_b128 v[238:241], v0 offset:8704
	v_add3_u32 v0, s19, v199, v196
	v_add3_u32 v0, v0, v200, v202
	ds_read_b64_tr_b16 v[142:143], v0 offset:9216
	ds_read_b64_tr_b16 v[144:145], v0 offset:9728
	ds_read_b64_tr_b16 v[134:135], v0 offset:10240
	ds_read_b64_tr_b16 v[136:137], v0 offset:10752
	ds_read_b64_tr_b16 v[138:139], v0 offset:13312
	ds_read_b64_tr_b16 v[140:141], v0 offset:13824
	ds_read_b64_tr_b16 v[130:131], v0 offset:14336
	ds_read_b64_tr_b16 v[132:133], v0 offset:14848
	s_waitcnt lgkmcnt(10)
	v_mfma_f32_32x32x16_bf16 v[34:49], v[118:121], v[78:81], v[34:49]
	s_waitcnt lgkmcnt(9)
	v_mfma_f32_32x32x16_bf16 v[50:65], v[114:117], v[110:113], v[50:65]
	ds_read_b64_tr_b16 v[126:127], v0 offset:11264
	ds_read_b64_tr_b16 v[128:129], v0 offset:11776
	ds_read_b64_tr_b16 v[118:119], v0 offset:12288
	ds_read_b64_tr_b16 v[120:121], v0 offset:12800
	ds_read_b64_tr_b16 v[122:123], v0 offset:15360
	ds_read_b64_tr_b16 v[124:125], v0 offset:15872
	ds_read_b64_tr_b16 v[114:115], v0 offset:16384
	ds_read_b64_tr_b16 v[116:117], v0 offset:16896
	s_waitcnt lgkmcnt(14)
	v_mfma_f32_32x32x16_bf16 v[34:49], v[238:241], v[110:113], v[34:49]
	s_cbranch_scc1 .LBB0_354
	v_cmp_le_i32_e32 vcc, v204, v235
	s_nop 9
	v_cndmask_b32_e32 v34, v180, v34, vcc
	v_cmp_lt_i32_e32 vcc, v203, v235
	s_nop 1
	v_cndmask_b32_e32 v51, v180, v51, vcc
	v_cmp_le_i32_e32 vcc, v203, v235
	s_nop 1
	v_cndmask_b32_e32 v50, v180, v50, vcc
	v_cmp_le_i32_e32 vcc, v205, v235
	s_nop 1
	v_cndmask_b32_e32 v35, v180, v35, vcc
	v_cmp_le_i32_e32 vcc, v206, v235
	s_nop 1
	v_cndmask_b32_e32 v52, v180, v52, vcc
	v_cmp_le_i32_e32 vcc, v207, v235
	s_nop 1
	v_cndmask_b32_e32 v36, v180, v36, vcc
	v_cmp_le_i32_e32 vcc, v208, v235
	s_nop 1
	v_cndmask_b32_e32 v53, v180, v53, vcc
	v_cmp_le_i32_e32 vcc, v209, v235
	s_nop 1
	v_cndmask_b32_e32 v37, v180, v37, vcc
	v_cmp_le_i32_e32 vcc, v210, v235
	s_nop 1
	v_cndmask_b32_e32 v54, v180, v54, vcc
	v_cmp_le_i32_e32 vcc, v211, v235
	s_nop 1
	v_cndmask_b32_e32 v38, v180, v38, vcc
	v_cmp_le_i32_e32 vcc, v212, v235
	s_nop 1
	v_cndmask_b32_e32 v55, v180, v55, vcc
	v_cmp_le_i32_e32 vcc, v213, v235
	s_nop 1
	v_cndmask_b32_e32 v39, v180, v39, vcc
	v_cmp_le_i32_e32 vcc, v214, v235
	s_nop 1
	v_cndmask_b32_e32 v56, v180, v56, vcc
	v_cmp_le_i32_e32 vcc, v215, v235
	s_nop 1
	v_cndmask_b32_e32 v40, v180, v40, vcc
	v_cmp_le_i32_e32 vcc, v216, v235
	s_nop 1
	v_cndmask_b32_e32 v57, v180, v57, vcc
	v_cmp_le_i32_e32 vcc, v217, v235
	s_nop 1
	v_cndmask_b32_e32 v41, v180, v41, vcc
	v_cmp_le_i32_e32 vcc, v218, v235
	s_nop 1
	v_cndmask_b32_e32 v58, v180, v58, vcc
	v_cmp_le_i32_e32 vcc, v219, v235
	s_nop 1
	v_cndmask_b32_e32 v42, v180, v42, vcc
	v_cmp_le_i32_e32 vcc, v220, v235
	s_nop 1
	v_cndmask_b32_e32 v59, v180, v59, vcc
	v_cmp_le_i32_e32 vcc, v221, v235
	s_nop 1
	v_cndmask_b32_e32 v43, v180, v43, vcc
	v_cmp_le_i32_e32 vcc, v222, v235
	s_nop 1
	v_cndmask_b32_e32 v60, v180, v60, vcc
	v_cmp_le_i32_e32 vcc, v223, v235
	s_nop 1
	v_cndmask_b32_e32 v44, v180, v44, vcc
	v_cmp_le_i32_e32 vcc, v224, v235
	s_nop 1
	v_cndmask_b32_e32 v61, v180, v61, vcc
	v_cmp_le_i32_e32 vcc, v225, v235
	s_nop 1
	v_cndmask_b32_e32 v45, v180, v45, vcc
	v_cmp_le_i32_e32 vcc, v226, v235
	s_nop 1
	v_cndmask_b32_e32 v62, v180, v62, vcc
	v_cmp_le_i32_e32 vcc, v227, v235
	s_nop 1
	v_cndmask_b32_e32 v46, v180, v46, vcc
	v_cmp_le_i32_e32 vcc, v228, v235
	s_nop 1
	v_cndmask_b32_e32 v63, v180, v63, vcc
	v_cmp_le_i32_e32 vcc, v229, v235
	s_nop 1
	v_cndmask_b32_e32 v47, v180, v47, vcc
	v_cmp_le_i32_e32 vcc, v230, v235
	s_nop 1
	v_cndmask_b32_e32 v64, v180, v64, vcc
	v_cmp_le_i32_e32 vcc, v231, v235
	s_nop 1
	v_cndmask_b32_e32 v48, v180, v48, vcc
	v_cmp_le_i32_e32 vcc, v232, v235
	s_nop 1
	v_cndmask_b32_e32 v65, v180, v65, vcc
	v_cmp_le_i32_e32 vcc, v233, v235
	s_nop 1
	v_cndmask_b32_e32 v49, v180, v49, vcc

; DI unsigned cvtpk(float lo, float hi) { f32x2_t v = {lo, hi}; bf16x2_t b = __builtin_convertvector(v, bf16x2_t); return __builtin_bit_cast(unsigned, b); }
; DI void qk_tile(const char* kb, const bf16x8 (&qr)[5], int r32, int hi, f32x16& x0, f32x16& x1) {
;     bf16x8 kf[10];
; #pragma unroll
;     for (int d0 = 0; d0 < 4; ++d0) {
;         kf[2 * d0] = *(const bf16x8*)(kb + (2 * d0 + hi) * 1024 + r32 * 16);
;         kf[2 * d0 + 1] = *(const bf16x8*)(kb + (2 * d0 + hi) * 1024 + 512 + r32 * 16);
;     }
;     kf[8] = *(const bf16x8*)(kb + 8192 + r32 * 16);
;     kf[9] = *(const bf16x8*)(kb + 8192 + 512 + r32 * 16);
;     asm volatile("s_waitcnt lgkmcnt(0)" ::: "memory");
; #pragma unroll
;     for (int i = 0; i < 16; ++i) { x0[i] = 0.f; x1[i] = 0.f; }
; #pragma unroll
;     for (int d0 = 0; d0 < 5; ++d0) { x0 = MFMA32(kf[2 * d0], qr[d0], x0); x1 = MFMA32(kf[2 * d0 + 1], qr[d0], x1); }
; }
; DI void v_load(const char* vb, int lane, int hi, bf16x8 (&vf)[8]) {
;     const lds_cptr vp = (lds_cptr)vb + ((lane >> 4) & 1) * 32 + (lane & 3) * 8 + (4 * hi + ((lane & 15) >> 2)) * 64;
; #pragma unroll
;     for (int ks = 0; ks < 4; ++ks) {
;         { const s16x4 lo = vtr(vp + ks * 1024), hh = vtr(vp + ks * 1024 + 512); vf[ks] = (bf16x8){lo[0], lo[1], lo[2], lo[3], hh[0], hh[1], hh[2], hh[3]}; }
;         { const s16x4 lo = vtr(vp + 4096 + ks * 1024), hh = vtr(vp + 4096 + ks * 1024 + 512); vf[4 + ks] = (bf16x8){lo[0], lo[1], lo[2], lo[3], hh[0], hh[1], hh[2], hh[3]}; }
;     }
;     asm volatile("" ::: "memory");
; }
; DI void pv_tile(const bf16x8 (&vf)[8], const f32x16& p0, const f32x16& p1, f32x16& o0, f32x16& o1) {
;     u32x4 w[4];
; #pragma unroll
;     for (int j = 0; j < 4; ++j) { w[0][j] = cvtpk(p0[2 * j], p0[2 * j + 1]); w[1][j] = cvtpk(p0[8 + 2 * j], p0[9 + 2 * j]);
;                                   w[2][j] = cvtpk(p1[2 * j], p1[2 * j + 1]); w[3][j] = cvtpk(p1[8 + 2 * j], p1[9 + 2 * j]); }
; #pragma unroll
;     for (int ks = 0; ks < 4; ++ks) { const bf16x8 pb = __builtin_bit_cast(bf16x8, w[ks]); o0 = MFMA32(vf[ks], pb, o0); o1 = MFMA32(vf[4 + ks], pb, o1); }
; }
; DI void mask_tile(f32x16& x0, f32x16& x1, int klo, int khi, int hi) {
; #pragma unroll
;     for (int i = 0; i < 16; ++i) { const int k = crow(i, hi); if (k < klo || k > khi) x0[i] = NEGX; if (k + 32 < klo || k + 32 > khi) x1[i] = NEGX; }
.LBB0_395:
	s_andn2_b64 vcc, exec, s[16:17]
	s_cbranch_vccnz .LBB0_401
	s_mulk_i32 s26, 0x4800
	s_add_i32 s16, s26, 0
	v_add_u32_e32 v0, s16, v198
	v_add_u32_e32 v111, v0, v199
	ds_read_b128 v[36:39], v111
	s_waitcnt vmcnt(4)
	ds_read_b128 v[40:43], v111 offset:512
	ds_read_b128 v[116:119], v111 offset:2048
	ds_read_b128 v[120:123], v111 offset:2560
	s_add_i32 s17, s23, 0xfffffec0
	s_cmp_le_i32 s17, s19
	s_waitcnt lgkmcnt(3)
	v_mfma_f32_32x32x16_bf16 v[52:67], v[36:39], v[84:87], 0
	s_waitcnt vmcnt(2) lgkmcnt(2)
	v_mfma_f32_32x32x16_bf16 v[36:51], v[40:43], v[84:87], 0
	s_waitcnt lgkmcnt(1)
	v_mfma_f32_32x32x16_bf16 v[52:67], v[116:119], v[88:91], v[52:67]
	s_waitcnt lgkmcnt(0)
	v_mfma_f32_32x32x16_bf16 v[36:51], v[120:123], v[88:91], v[36:51]
	ds_read_b128 v[116:119], v111 offset:4096
	ds_read_b128 v[120:123], v111 offset:4608
	s_waitcnt lgkmcnt(1)
	v_mfma_f32_32x32x16_bf16 v[52:67], v[116:119], v[92:95], v[52:67]
	s_waitcnt lgkmcnt(0)
	v_mfma_f32_32x32x16_bf16 v[36:51], v[120:123], v[92:95], v[36:51]
	ds_read_b128 v[116:119], v111 offset:6144
	ds_read_b128 v[120:123], v111 offset:6656
	s_waitcnt lgkmcnt(1)
	v_mfma_f32_32x32x16_bf16 v[52:67], v[116:119], v[96:99], v[52:67]
	ds_read_b128 v[116:119], v0 offset:8192
	ds_read_b128 v[238:241], v0 offset:8704
	v_add3_u32 v0, s16, v200, v197
	v_add3_u32 v0, v0, v201, v203
	ds_read_b64_tr_b16 v[144:145], v0 offset:9216
	ds_read_b64_tr_b16 v[146:147], v0 offset:9728
	ds_read_b64_tr_b16 v[136:137], v0 offset:10240
	ds_read_b64_tr_b16 v[138:139], v0 offset:10752
	ds_read_b64_tr_b16 v[140:141], v0 offset:13312
	ds_read_b64_tr_b16 v[142:143], v0 offset:13824
	ds_read_b64_tr_b16 v[132:133], v0 offset:14336
	ds_read_b64_tr_b16 v[134:135], v0 offset:14848
	s_waitcnt lgkmcnt(10)
	v_mfma_f32_32x32x16_bf16 v[36:51], v[120:123], v[96:99], v[36:51]
	s_waitcnt lgkmcnt(9)
	v_mfma_f32_32x32x16_bf16 v[52:67], v[116:119], v[112:115], v[52:67]
	ds_read_b64_tr_b16 v[128:129], v0 offset:11264
	ds_read_b64_tr_b16 v[130:131], v0 offset:11776
	ds_read_b64_tr_b16 v[120:121], v0 offset:12288
	ds_read_b64_tr_b16 v[122:123], v0 offset:12800
	ds_read_b64_tr_b16 v[124:125], v0 offset:15360
	ds_read_b64_tr_b16 v[126:127], v0 offset:15872
	ds_read_b64_tr_b16 v[116:117], v0 offset:16384
	ds_read_b64_tr_b16 v[118:119], v0 offset:16896
	s_waitcnt lgkmcnt(14)
	v_mfma_f32_32x32x16_bf16 v[36:51], v[238:241], v[112:115], v[36:51]
	s_cbranch_scc1 .LBB0_398
	v_cmp_le_i32_e32 vcc, v205, v236
	s_nop 9
	v_cndmask_b32_e32 v36, v180, v36, vcc
	v_cmp_lt_i32_e32 vcc, v204, v236
	s_nop 1
	v_cndmask_b32_e32 v53, v180, v53, vcc
	v_cmp_le_i32_e32 vcc, v204, v236
	s_nop 1
	v_cndmask_b32_e32 v52, v180, v52, vcc
	v_cmp_le_i32_e32 vcc, v206, v236
	s_nop 1
	v_cndmask_b32_e32 v37, v180, v37, vcc
	v_cmp_le_i32_e32 vcc, v207, v236
	s_nop 1
	v_cndmask_b32_e32 v54, v180, v54, vcc
	v_cmp_le_i32_e32 vcc, v208, v236
	s_nop 1
	v_cndmask_b32_e32 v38, v180, v38, vcc
	v_cmp_le_i32_e32 vcc, v209, v236
	s_nop 1
	v_cndmask_b32_e32 v55, v180, v55, vcc
	v_cmp_le_i32_e32 vcc, v210, v236
	s_nop 1
	v_cndmask_b32_e32 v39, v180, v39, vcc
	v_cmp_le_i32_e32 vcc, v211, v236
	s_nop 1
	v_cndmask_b32_e32 v56, v180, v56, vcc
	v_cmp_le_i32_e32 vcc, v212, v236
	s_nop 1
	v_cndmask_b32_e32 v40, v180, v40, vcc
	v_cmp_le_i32_e32 vcc, v213, v236
	s_nop 1
	v_cndmask_b32_e32 v57, v180, v57, vcc
	v_cmp_le_i32_e32 vcc, v214, v236
	s_nop 1
	v_cndmask_b32_e32 v41, v180, v41, vcc
	v_cmp_le_i32_e32 vcc, v215, v236
	s_nop 1
	v_cndmask_b32_e32 v58, v180, v58, vcc
	v_cmp_le_i32_e32 vcc, v216, v236
	s_nop 1
	v_cndmask_b32_e32 v42, v180, v42, vcc
	v_cmp_le_i32_e32 vcc, v217, v236
	s_nop 1
	v_cndmask_b32_e32 v59, v180, v59, vcc
	v_cmp_le_i32_e32 vcc, v218, v236
	s_nop 1
	v_cndmask_b32_e32 v43, v180, v43, vcc
	v_cmp_le_i32_e32 vcc, v219, v236
	s_nop 1
	v_cndmask_b32_e32 v60, v180, v60, vcc
	v_cmp_le_i32_e32 vcc, v220, v236
	s_nop 1
	v_cndmask_b32_e32 v44, v180, v44, vcc
	v_cmp_le_i32_e32 vcc, v221, v236
	s_nop 1
	v_cndmask_b32_e32 v61, v180, v61, vcc
	v_cmp_le_i32_e32 vcc, v222, v236
	s_nop 1
	v_cndmask_b32_e32 v45, v180, v45, vcc
	v_cmp_le_i32_e32 vcc, v223, v236
	s_nop 1
	v_cndmask_b32_e32 v62, v180, v62, vcc
	v_cmp_le_i32_e32 vcc, v224, v236
	s_nop 1
	v_cndmask_b32_e32 v46, v180, v46, vcc
	v_cmp_le_i32_e32 vcc, v225, v236
	s_nop 1
	v_cndmask_b32_e32 v63, v180, v63, vcc
	v_cmp_le_i32_e32 vcc, v226, v236
	s_nop 1
	v_cndmask_b32_e32 v47, v180, v47, vcc
	v_cmp_le_i32_e32 vcc, v227, v236
	s_nop 1
	v_cndmask_b32_e32 v64, v180, v64, vcc
	v_cmp_le_i32_e32 vcc, v228, v236
	s_nop 1
	v_cndmask_b32_e32 v48, v180, v48, vcc
	v_cmp_le_i32_e32 vcc, v229, v236
	s_nop 1
	v_cndmask_b32_e32 v65, v180, v65, vcc
	v_cmp_le_i32_e32 vcc, v230, v236
	s_nop 1
	v_cndmask_b32_e32 v49, v180, v49, vcc
	v_cmp_le_i32_e32 vcc, v231, v236
	s_nop 1
	v_cndmask_b32_e32 v66, v180, v66, vcc
	v_cmp_le_i32_e32 vcc, v232, v236
	s_nop 1
	v_cndmask_b32_e32 v50, v180, v50, vcc
	v_cmp_le_i32_e32 vcc, v233, v236
	s_nop 1
	v_cndmask_b32_e32 v67, v180, v67, vcc
	v_cmp_le_i32_e32 vcc, v234, v236
	s_nop 1
	v_cndmask_b32_e32 v51, v180, v51, vcc

; DI void qk_tile(const char* kb, const bf16x8 (&qr)[5], int r32, int hi, f32x16& x0, f32x16& x1) {
;     bf16x8 kf[10];
; #pragma unroll
;     for (int d0 = 0; d0 < 4; ++d0) {
;         kf[2 * d0] = *(const bf16x8*)(kb + (2 * d0 + hi) * 1024 + r32 * 16);
;         kf[2 * d0 + 1] = *(const bf16x8*)(kb + (2 * d0 + hi) * 1024 + 512 + r32 * 16);
;     }
;     kf[8] = *(const bf16x8*)(kb + 8192 + r32 * 16);
;     kf[9] = *(const bf16x8*)(kb + 8192 + 512 + r32 * 16);
;     asm volatile("s_waitcnt lgkmcnt(0)" ::: "memory");
; #pragma unroll
;     for (int i = 0; i < 16; ++i) { x0[i] = 0.f; x1[i] = 0.f; }
; #pragma unroll
;     for (int d0 = 0; d0 < 5; ++d0) { x0 = MFMA32(kf[2 * d0], qr[d0], x0); x1 = MFMA32(kf[2 * d0 + 1], qr[d0], x1); }
; }
; DI void v_load(const char* vb, int lane, int hi, bf16x8 (&vf)[8]) {
;     const lds_cptr vp = (lds_cptr)vb + ((lane >> 4) & 1) * 32 + (lane & 3) * 8 + (4 * hi + ((lane & 15) >> 2)) * 64;
; #pragma unroll
;     for (int ks = 0; ks < 4; ++ks) {
;         { const s16x4 lo = vtr(vp + ks * 1024), hh = vtr(vp + ks * 1024 + 512); vf[ks] = (bf16x8){lo[0], lo[1], lo[2], lo[3], hh[0], hh[1], hh[2], hh[3]}; }
;         { const s16x4 lo = vtr(vp + 4096 + ks * 1024), hh = vtr(vp + 4096 + ks * 1024 + 512); vf[4 + ks] = (bf16x8){lo[0], lo[1], lo[2], lo[3], hh[0], hh[1], hh[2], hh[3]}; }
;     }
;     asm volatile("" ::: "memory");
; }
; DI void pv_tile(const bf16x8 (&vf)[8], const f32x16& p0, const f32x16& p1, f32x16& o0, f32x16& o1) {
;     u32x4 w[4];
; #pragma unroll
;     for (int j = 0; j < 4; ++j) { w[0][j] = cvtpk(p0[2 * j], p0[2 * j + 1]); w[1][j] = cvtpk(p0[8 + 2 * j], p0[9 + 2 * j]);
;                                   w[2][j] = cvtpk(p1[2 * j], p1[2 * j + 1]); w[3][j] = cvtpk(p1[8 + 2 * j], p1[9 + 2 * j]); }
; #pragma unroll
;     for (int ks = 0; ks < 4; ++ks) { const bf16x8 pb = __builtin_bit_cast(bf16x8, w[ks]); o0 = MFMA32(vf[ks], pb, o0); o1 = MFMA32(vf[4 + ks], pb, o1); }
; }
; DI void mask_tile(f32x16& x0, f32x16& x1, int klo, int khi, int hi) {
; #pragma unroll
;     for (int i = 0; i < 16; ++i) { const int k = crow(i, hi); if (k < klo || k > khi) x0[i] = NEGX; if (k + 32 < klo || k + 32 > khi) x1[i] = NEGX; }
; }
; DI float tile_max(const f32x16& x0, const f32x16& x1) {
;     float ma = __builtin_fmaxf(x0[0], x1[0]), mb = __builtin_fmaxf(x0[1], x1[1]);
; #pragma unroll
.LBB0_488:
	v_add_u32_e32 v44, v34, v166
	ds_read_b128 v[2:5], v44
	ds_read_b128 v[18:21], v44 offset:512
	ds_read_b128 v[36:39], v44 offset:2048
	ds_read_b128 v[40:43], v44 offset:2560
	v_and_b32_e32 v46, 64, v181
	v_xor_b32_e32 v45, 32, v181
	s_waitcnt lgkmcnt(3)
	v_mfma_f32_32x32x16_bf16 v[2:17], v[2:5], v[68:71], 0
	v_add_u32_e32 v133, 64, v46
	v_cmp_lt_i32_e32 vcc, v45, v133
	v_cmp_lt_i32_e64 s[6:7], v167, v35
	v_cmp_le_i32_e64 s[8:9], v169, v35
	v_cmp_le_i32_e64 s[0:1], v168, v35
	v_cmp_le_i32_e64 s[14:15], v170, v35
	v_cmp_le_i32_e64 s[18:19], v186, v35
	s_waitcnt lgkmcnt(2)
	v_mfma_f32_32x32x16_bf16 v[18:33], v[18:21], v[68:71], 0
	v_cmp_le_i32_e64 s[20:21], v187, v35
	v_cmp_le_i32_e64 s[16:17], v171, v35
	v_cmp_le_i32_e64 s[22:23], v188, v35
	v_cmp_le_i32_e64 s[26:27], v190, v35
	v_cmp_le_i32_e64 s[28:29], v191, v35
	v_cmp_le_i32_e64 s[24:25], v189, v35
	v_cmp_le_i32_e64 s[30:31], v192, v35
	s_waitcnt lgkmcnt(1)
	v_mfma_f32_32x32x16_bf16 v[2:17], v[36:39], v[72:75], v[2:17]
	v_cmp_le_i32_e64 s[36:37], v194, v35
	v_cmp_le_i32_e64 s[38:39], v195, v35
	v_cmp_le_i32_e64 s[34:35], v193, v35
	v_cmp_le_i32_e64 s[40:41], v196, v35
	v_cmp_le_i32_e64 s[44:45], v198, v35
	v_cmp_le_i32_e64 s[46:47], v199, v35
	v_cmp_le_i32_e64 s[42:43], v197, v35
	s_waitcnt lgkmcnt(0)
	v_mfma_f32_32x32x16_bf16 v[18:33], v[40:43], v[72:75], v[18:33]
	ds_read_b128 v[36:39], v44 offset:4096
	ds_read_b128 v[40:43], v44 offset:4608
	v_cmp_le_i32_e64 s[48:49], v200, v35
	v_cmp_le_i32_e64 s[52:53], v202, v35
	v_cmp_le_i32_e64 s[54:55], v203, v35
	v_cmp_le_i32_e64 s[50:51], v201, v35
	v_cmp_le_i32_e64 s[56:57], v204, v35
	v_cmp_le_i32_e64 s[60:61], v206, v35
	s_waitcnt lgkmcnt(1)
	v_mfma_f32_32x32x16_bf16 v[2:17], v[36:39], v[76:79], v[2:17]
	v_cmp_le_i32_e64 s[62:63], v207, v35
	v_cmp_le_i32_e64 s[58:59], v205, v35
	v_cmp_le_i32_e64 s[64:65], v208, v35
	v_cmp_le_i32_e64 s[68:69], v210, v35
	v_cmp_le_i32_e64 s[70:71], v211, v35
	v_cmp_le_i32_e64 s[66:67], v209, v35
	v_mov_b32_e32 v47, v0
	s_waitcnt lgkmcnt(0)
	v_mfma_f32_32x32x16_bf16 v[18:33], v[40:43], v[76:79], v[18:33]
	ds_read_b128 v[36:39], v44 offset:6144
	ds_read_b128 v[40:43], v44 offset:6656
	v_mov_b32_e32 v44, v142
	v_max_f32_e32 v0, v44, v44
	s_add_i32 s91, s91, -1
	s_cmp_eq_u32 s91, 0
	s_waitcnt lgkmcnt(1)
	v_mfma_f32_32x32x16_bf16 v[2:17], v[36:39], v[80:83], v[2:17]
	ds_read_b128 v[36:39], v34 offset:8192
	s_waitcnt lgkmcnt(1)
	v_mfma_f32_32x32x16_bf16 v[18:33], v[40:43], v[80:83], v[18:33]
	ds_read_b128 v[40:43], v34 offset:8704
	v_add_u32_e32 v34, 0x4800, v34
	s_waitcnt lgkmcnt(1)
	v_mfma_f32_32x32x16_bf16 v[2:17], v[36:39], v[96:99], v[2:17]
	v_cndmask_b32_e32 v36, v181, v45, vcc
	v_lshlrev_b32_e32 v212, 2, v36
	v_cmp_le_i32_e32 vcc, v167, v35
	v_subrev_u32_e32 v35, 64, v35
	s_waitcnt lgkmcnt(0)
	v_mfma_f32_32x32x16_bf16 v[18:33], v[40:43], v[96:99], v[18:33]
	s_nop 5
	v_cndmask_b32_e64 v3, v180, v3, s[6:7]
	v_max_f32_e32 v37, v3, v3
	v_cndmask_b32_e32 v2, v180, v2, vcc
	v_cndmask_b32_e64 v4, v180, v4, s[14:15]
	v_cndmask_b32_e64 v5, v180, v5, s[18:19]
	v_cndmask_b32_e64 v6, v180, v6, s[22:23]
	v_cndmask_b32_e64 v7, v180, v7, s[26:27]
	v_cndmask_b32_e64 v19, v180, v19, s[8:9]
	v_max_f32_e32 v36, v19, v19
	v_cndmask_b32_e64 v18, v180, v18, s[0:1]
	v_cndmask_b32_e64 v21, v180, v21, s[20:21]
	v_max_f32_e32 v36, v37, v36
	v_cndmask_b32_e64 v20, v180, v20, s[16:17]
	v_cndmask_b32_e64 v23, v180, v23, s[28:29]
	v_max3_f32 v38, v2, v18, v4
	v_max3_f32 v36, v36, v5, v21
	v_cndmask_b32_e64 v22, v180, v22, s[24:25]
	v_cndmask_b32_e64 v8, v180, v8, s[30:31]
	v_cndmask_b32_e64 v9, v180, v9, s[36:37]
	v_cndmask_b32_e64 v25, v180, v25, s[38:39]
	v_max3_f32 v37, v38, v20, v6
	v_max3_f32 v36, v36, v7, v23
	v_cndmask_b32_e64 v24, v180, v24, s[34:35]
	v_cndmask_b32_e64 v10, v180, v10, s[40:41]
	v_cndmask_b32_e64 v11, v180, v11, s[44:45]
	v_cndmask_b32_e64 v27, v180, v27, s[46:47]
	v_max3_f32 v37, v37, v22, v8
	v_max3_f32 v36, v36, v9, v25
	v_cndmask_b32_e64 v26, v180, v26, s[42:43]
	v_cndmask_b32_e64 v12, v180, v12, s[48:49]
	v_cndmask_b32_e64 v13, v180, v13, s[52:53]
	v_cndmask_b32_e64 v29, v180, v29, s[54:55]
	v_max3_f32 v37, v37, v24, v10
	v_max3_f32 v36, v36, v11, v27
	v_cndmask_b32_e64 v28, v180, v28, s[50:51]
	v_cndmask_b32_e64 v14, v180, v14, s[56:57]
	v_cndmask_b32_e64 v15, v180, v15, s[60:61]
	v_cndmask_b32_e64 v31, v180, v31, s[62:63]
	v_max3_f32 v37, v37, v26, v12
	v_max3_f32 v36, v36, v13, v29
	v_cndmask_b32_e64 v30, v180, v30, s[58:59]
	v_cndmask_b32_e64 v16, v180, v16, s[64:65]
	v_cndmask_b32_e64 v17, v180, v17, s[68:69]
	v_cndmask_b32_e64 v33, v180, v33, s[70:71]
	v_max3_f32 v37, v37, v28, v14
	v_max3_f32 v36, v36, v15, v31
	v_cndmask_b32_e64 v32, v180, v32, s[66:67]
	v_max3_f32 v37, v37, v30, v16
	v_max3_f32 v36, v36, v17, v33
	v_max3_f32 v36, v37, v32, v36
	v_mov_b32_e32 v37, v36
	v_mov_b32_e32 v251, v36
	s_nop 1
	v_permlane32_swap_b32_e32 v37, v251
	s_waitcnt lgkmcnt(0)
; DI float ex2(float x) { return __builtin_amdgcn_exp2f(x); }
; DI void smx_stats(const f32x16& x0, const f32x16& x1, float& m, float& l) {
;     const float mn = fmaxf(m, tile_max(x0, x1) * C2);
;     l *= ex2(m - mn); m = mn;
;     float s = 0.f;
; #pragma unroll
;     for (int i = 0; i < 16; ++i) s += ex2(fmaf(x0[i], C2, -mn)) + ex2(fmaf(x1[i], C2, -mn));
;     l += s;
; }
; DI void nsa_unit(const bf16* PR, const float* AUX, const bf16* KC, const bf16* VC, bf16* MIX, char* sm, int b, int qb) {
;     ...
;         for (int it = 0; it < ntc; ++it) { const char* cb = sm + it * STG; f32x16 x0, x1; qk_tile(cb, qr, r32, hi, x0, x1); mask_tile(x0, x1, 0, khc - 64 * it, hi); smx_stats(x0, x1, m, l); }
;         const float lt = l + __shfl_xor(l, 32); const float invl = lt > 0.f ? 1.f / lt : 0.f;
;         float carry = 0.f;
; #pragma unroll
;         for (int i = 0; i < 16; ++i) { o0[i] = 0.f; o1[i] = 0.f; }
	v_max_f32_e32 v37, v37, v251
	v_max_f32_e32 v36, v36, v37
	v_mul_f32_e32 v36, 0x3e38aa3b, v36
	v_max_f32_e32 v142, v0, v36
	v_fma_f32 v0, v2, s92, -v142
	v_fma_f32 v2, v18, s92, -v142
	v_fma_f32 v3, v3, s92, -v142
	v_fma_f32 v18, v19, s92, -v142
	v_fma_f32 v19, v20, s92, -v142
	v_fma_f32 v20, v21, s92, -v142
	v_fma_f32 v21, v22, s92, -v142
	v_fma_f32 v22, v23, s92, -v142
	v_fma_f32 v23, v24, s92, -v142
	v_fma_f32 v24, v25, s92, -v142
	v_fma_f32 v25, v26, s92, -v142
	v_fma_f32 v26, v27, s92, -v142
	v_fma_f32 v27, v28, s92, -v142
	v_fma_f32 v28, v29, s92, -v142
	v_fma_f32 v29, v30, s92, -v142
	v_fma_f32 v30, v31, s92, -v142
	v_fma_f32 v31, v32, s92, -v142
	v_fma_f32 v32, v33, s92, -v142
	v_exp_f32_e32 v33, v0
	v_exp_f32_e32 v36, v2
	v_exp_f32_e32 v2, v3
	v_exp_f32_e32 v0, v18
	v_fma_f32 v4, v4, s92, -v142
	v_add_f32_e32 v3, v33, v36
	v_fma_f32 v5, v5, s92, -v142
	v_pk_add_f32 v[2:3], v[2:3], v[0:1]
	v_exp_f32_e32 v18, v4
	v_exp_f32_e32 v19, v19
	v_pk_add_f32 v[2:3], v[2:3], v[2:3] op_sel_hi:[0,1]
	v_exp_f32_e32 v4, v5
	v_exp_f32_e32 v2, v20
	v_add_f32_e32 v5, v18, v19
	v_fma_f32 v6, v6, s92, -v142
	v_fma_f32 v7, v7, s92, -v142
	v_pk_add_f32 v[2:3], v[4:5], v[2:3]
	v_exp_f32_e32 v37, v6
	v_exp_f32_e32 v21, v21
	v_pk_add_f32 v[2:3], v[2:3], v[2:3] op_sel_hi:[0,1]
	v_exp_f32_e32 v6, v7
	v_exp_f32_e32 v2, v22
	v_add_f32_e32 v7, v37, v21
	v_fma_f32 v8, v8, s92, -v142
	v_fma_f32 v9, v9, s92, -v142
	v_pk_add_f32 v[2:3], v[6:7], v[2:3]
	v_exp_f32_e32 v38, v8
	v_exp_f32_e32 v23, v23
	v_pk_add_f32 v[2:3], v[2:3], v[2:3] op_sel_hi:[0,1]
	v_exp_f32_e32 v8, v9
	v_exp_f32_e32 v2, v24
	v_add_f32_e32 v9, v38, v23
	v_fma_f32 v10, v10, s92, -v142
	v_fma_f32 v11, v11, s92, -v142
	v_pk_add_f32 v[2:3], v[8:9], v[2:3]
	v_exp_f32_e32 v0, v10
	v_exp_f32_e32 v10, v25
	v_pk_add_f32 v[2:3], v[2:3], v[2:3] op_sel_hi:[0,1]
	v_exp_f32_e32 v4, v11
	v_exp_f32_e32 v2, v26
	v_add_f32_e32 v5, v0, v10
	v_fma_f32 v12, v12, s92, -v142
	v_fma_f32 v13, v13, s92, -v142
	v_pk_add_f32 v[2:3], v[4:5], v[2:3]
	v_exp_f32_e32 v11, v12
	v_exp_f32_e32 v7, v27
	v_pk_add_f32 v[2:3], v[2:3], v[2:3] op_sel_hi:[0,1]
	v_exp_f32_e32 v6, v13
	v_exp_f32_e32 v2, v28
	v_add_f32_e32 v7, v11, v7
	v_fma_f32 v14, v14, s92, -v142
	v_fma_f32 v15, v15, s92, -v142
	v_pk_add_f32 v[2:3], v[6:7], v[2:3]
	v_exp_f32_e32 v8, v14
	v_exp_f32_e32 v9, v29
	v_pk_add_f32 v[2:3], v[2:3], v[2:3] op_sel_hi:[0,1]
	v_exp_f32_e32 v4, v15
	v_exp_f32_e32 v2, v30
	v_add_f32_e32 v5, v8, v9
	v_fma_f32 v16, v16, s92, -v142
	v_fma_f32 v17, v17, s92, -v142
	v_pk_add_f32 v[2:3], v[4:5], v[2:3]
	v_exp_f32_e32 v0, v16
	v_exp_f32_e32 v7, v31
	v_pk_add_f32 v[2:3], v[2:3], v[2:3] op_sel_hi:[0,1]
	v_exp_f32_e32 v6, v17
	v_exp_f32_e32 v2, v32
	v_sub_f32_e32 v4, v44, v142
	v_exp_f32_e32 v4, v4
	v_add_f32_e32 v7, v0, v7
	v_pk_add_f32 v[2:3], v[6:7], v[2:3]
	s_nop 0
	v_add_f32_e32 v0, v2, v3
	v_fmac_f32_e32 v0, v47, v4
	s_cbranch_scc0 .LBB0_488
	ds_bpermute_b32 v2, v212, v0
	v_lshlrev_b32_e32 v215, 4, v149
	v_lshlrev_b32_e32 v4, 1, v149
	v_lshlrev_b32_e32 v214, 8, v160
	v_and_b32_e32 v216, 0xc0, v215
	s_waitcnt lgkmcnt(0)
	v_add_f32_e32 v0, v0, v2
	v_div_scale_f32 v2, s[0:1], v0, v0, 1.0
	v_rcp_f32_e32 v3, v2
	v_div_scale_f32 v5, vcc, 1.0, v0, 1.0
	s_add_i32 s0, s72, s81
	v_fma_f32 v6, -v2, v3, 1.0
	v_fmac_f32_e32 v3, v6, v3
	v_mul_f32_e32 v6, v5, v3
	v_fma_f32 v7, -v2, v6, v5
	v_fmac_f32_e32 v6, v7, v3
	v_fma_f32 v2, -v2, v6, v5
	v_div_fmas_f32 v2, v2, v3, v6
	v_div_fixup_f32 v2, v2, v0, 1.0
	v_cmp_lt_f32_e32 vcc, 0, v0
	v_add_u32_e32 v0, s0, v135
	s_movk_i32 s0, 0x84
	v_mov_b32_e32 v158, 0
	v_cndmask_b32_e32 v66, 0, v2, vcc
	v_and_b32_e32 v213, 32, v4
	v_mul_lo_u32 v0, v0, s0
	s_mov_b32 s0, 0xb000
	v_or_b32_e32 v2, v214, v216
	v_mov_b32_e32 v67, v66
	v_add3_u32 v0, v0, v167, s0
	v_or3_b32 v143, v2, v213, v163
	v_or_b32_e32 v145, 0x2000, v165
	v_add_u32_e32 v146, v166, v165
	v_mov_b32_e32 v2, 0
	v_mov_b32_e32 v3, v158
	v_mov_b32_e32 v4, v158
	v_mov_b32_e32 v5, v158
	v_mov_b32_e32 v6, v158
	v_mov_b32_e32 v7, v158
	v_mov_b32_e32 v8, v158
	v_mov_b32_e32 v9, v158
	v_mov_b32_e32 v10, v158
	v_mov_b32_e32 v11, v158
	v_mov_b32_e32 v12, v158
	v_mov_b32_e32 v13, v158
	v_mov_b32_e32 v14, v158
	v_mov_b32_e32 v15, v158
	v_mov_b32_e32 v16, v158
	v_mov_b32_e32 v17, v158
	v_mov_b32_e32 v18, 0
	v_mov_b32_e32 v19, v158
	v_mov_b32_e32 v20, v158
	v_mov_b32_e32 v21, v158
	v_mov_b32_e32 v22, v158
	v_mov_b32_e32 v23, v158
	v_mov_b32_e32 v24, v158
	v_mov_b32_e32 v25, v158
	v_mov_b32_e32 v26, v158
	v_mov_b32_e32 v27, v158
	v_mov_b32_e32 v28, v158
	v_mov_b32_e32 v29, v158
	v_mov_b32_e32 v30, v158
	v_mov_b32_e32 v31, v158
	v_mov_b32_e32 v32, v158
	v_mov_b32_e32 v33, v158
; DI unsigned cvtpk(float lo, float hi) { f32x2_t v = {lo, hi}; bf16x2_t b = __builtin_convertvector(v, bf16x2_t); return __builtin_bit_cast(unsigned, b); }
; DI void qk_tile(const char* kb, const bf16x8 (&qr)[5], int r32, int hi, f32x16& x0, f32x16& x1) {
;     bf16x8 kf[10];
; #pragma unroll
;     for (int d0 = 0; d0 < 4; ++d0) {
;         kf[2 * d0] = *(const bf16x8*)(kb + (2 * d0 + hi) * 1024 + r32 * 16);
;         kf[2 * d0 + 1] = *(const bf16x8*)(kb + (2 * d0 + hi) * 1024 + 512 + r32 * 16);
;     }
;     kf[8] = *(const bf16x8*)(kb + 8192 + r32 * 16);
;     kf[9] = *(const bf16x8*)(kb + 8192 + 512 + r32 * 16);
;     asm volatile("s_waitcnt lgkmcnt(0)" ::: "memory");
; #pragma unroll
;     for (int i = 0; i < 16; ++i) { x0[i] = 0.f; x1[i] = 0.f; }
; #pragma unroll
;     for (int d0 = 0; d0 < 5; ++d0) { x0 = MFMA32(kf[2 * d0], qr[d0], x0); x1 = MFMA32(kf[2 * d0 + 1], qr[d0], x1); }
; }
; DI void v_load(const char* vb, int lane, int hi, bf16x8 (&vf)[8]) {
;     const lds_cptr vp = (lds_cptr)vb + ((lane >> 4) & 1) * 32 + (lane & 3) * 8 + (4 * hi + ((lane & 15) >> 2)) * 64;
; #pragma unroll
;     for (int ks = 0; ks < 4; ++ks) {
;         { const s16x4 lo = vtr(vp + ks * 1024), hh = vtr(vp + ks * 1024 + 512); vf[ks] = (bf16x8){lo[0], lo[1], lo[2], lo[3], hh[0], hh[1], hh[2], hh[3]}; }
;         { const s16x4 lo = vtr(vp + 4096 + ks * 1024), hh = vtr(vp + 4096 + ks * 1024 + 512); vf[4 + ks] = (bf16x8){lo[0], lo[1], lo[2], lo[3], hh[0], hh[1], hh[2], hh[3]}; }
;     }
;     asm volatile("" ::: "memory");
; }
; DI void pv_tile(const bf16x8 (&vf)[8], const f32x16& p0, const f32x16& p1, f32x16& o0, f32x16& o1) {
;     u32x4 w[4];
; #pragma unroll
;     for (int j = 0; j < 4; ++j) { w[0][j] = cvtpk(p0[2 * j], p0[2 * j + 1]); w[1][j] = cvtpk(p0[8 + 2 * j], p0[9 + 2 * j]);
;                                   w[2][j] = cvtpk(p1[2 * j], p1[2 * j + 1]); w[3][j] = cvtpk(p1[8 + 2 * j], p1[9 + 2 * j]); }
; #pragma unroll
;     for (int ks = 0; ks < 4; ++ks) { const bf16x8 pb = __builtin_bit_cast(bf16x8, w[ks]); o0 = MFMA32(vf[ks], pb, o0); o1 = MFMA32(vf[4 + ks], pb, o1); }
; }
; DI void mask_tile(f32x16& x0, f32x16& x1, int klo, int khi, int hi) {
; #pragma unroll
;     for (int i = 0; i < 16; ++i) { const int k = crow(i, hi); if (k < klo || k > khi) x0[i] = NEGX; if (k + 32 < klo || k + 32 > khi) x1[i] = NEGX; }
.LBB0_490:
	v_add_u32_e32 v42, 0, v146
	ds_read_b128 v[34:37], v42
	ds_read_b128 v[38:41], v42 offset:512
	ds_read_b128 v[100:103], v42 offset:2048
	ds_read_b128 v[104:107], v42 offset:2560
	ds_read_b128 v[108:111], v42 offset:4096
	ds_read_b128 v[112:115], v42 offset:4608
	ds_read_b128 v[116:119], v42 offset:6144
	ds_read_b128 v[120:123], v42 offset:6656
	v_add_u32_e32 v42, 0, v145
	ds_read_b128 v[124:127], v42
	ds_read_b128 v[128:131], v42 offset:512
	s_waitcnt lgkmcnt(9)
	v_mfma_f32_32x32x16_bf16 v[50:65], v[34:37], v[68:71], 0
	v_cmp_le_i32_e32 vcc, v167, v136
	v_cmp_le_i32_e64 s[0:1], v168, v136
	v_add_u32_e32 v231, 0, v0
	s_add_i32 s33, s33, -1
	v_add_u32_e32 v0, 64, v0
	v_add_u32_e32 v145, 0x4800, v145
	s_waitcnt lgkmcnt(8)
	v_mfma_f32_32x32x16_bf16 v[34:49], v[38:41], v[68:71], 0
	v_add_u32_e32 v146, 0x4800, v146
	s_cmp_eq_u32 s33, 0
	s_waitcnt lgkmcnt(7)
	v_mfma_f32_32x32x16_bf16 v[50:65], v[100:103], v[72:75], v[50:65]
	s_waitcnt lgkmcnt(6)
	v_mfma_f32_32x32x16_bf16 v[34:49], v[104:107], v[72:75], v[34:49]
	s_waitcnt lgkmcnt(5)
	v_mfma_f32_32x32x16_bf16 v[50:65], v[108:111], v[76:79], v[50:65]
	s_waitcnt lgkmcnt(4)
	v_mfma_f32_32x32x16_bf16 v[34:49], v[112:115], v[76:79], v[34:49]
	s_waitcnt lgkmcnt(3)
	v_mfma_f32_32x32x16_bf16 v[50:65], v[116:119], v[80:83], v[50:65]
	s_waitcnt lgkmcnt(2)
	v_mfma_f32_32x32x16_bf16 v[34:49], v[120:123], v[80:83], v[34:49]
	s_waitcnt lgkmcnt(1)
	v_mfma_f32_32x32x16_bf16 v[50:65], v[124:127], v[96:99], v[50:65]
	s_waitcnt lgkmcnt(0)
	v_mfma_f32_32x32x16_bf16 v[34:49], v[128:131], v[96:99], v[34:49]
	v_add_u32_e32 v130, 0, v143
	ds_read_b64_tr_b16 v[100:101], v130 offset:9216
	ds_read_b64_tr_b16 v[102:103], v130 offset:9728
	ds_read_b64_tr_b16 v[104:105], v130 offset:13312
	ds_read_b64_tr_b16 v[106:107], v130 offset:13824
	ds_read_b64_tr_b16 v[108:109], v130 offset:10240
	ds_read_b64_tr_b16 v[110:111], v130 offset:10752
	ds_read_b64_tr_b16 v[112:113], v130 offset:14336
	ds_read_b64_tr_b16 v[114:115], v130 offset:14848
	ds_read_b64_tr_b16 v[116:117], v130 offset:11264
	ds_read_b64_tr_b16 v[118:119], v130 offset:11776
	ds_read_b64_tr_b16 v[120:121], v130 offset:15360
	ds_read_b64_tr_b16 v[122:123], v130 offset:15872
	ds_read_b64_tr_b16 v[124:125], v130 offset:12288
	ds_read_b64_tr_b16 v[126:127], v130 offset:12800
	ds_read_b64_tr_b16 v[128:129], v130 offset:16384
	ds_read_b64_tr_b16 v[130:131], v130 offset:16896
	v_add_u32_e32 v143, 0x4800, v143
	v_cndmask_b32_e64 v147, v180, v34, s[0:1]
	v_cndmask_b32_e32 v34, v180, v50, vcc
	v_cmp_le_i32_e32 vcc, v169, v136
	v_cmp_lt_i32_e64 s[0:1], v167, v136
	v_fma_f32 v34, v34, s92, -v142
	v_cndmask_b32_e32 v50, v180, v35, vcc
	v_cmp_le_i32_e32 vcc, v170, v136
	v_cndmask_b32_e64 v51, v180, v51, s[0:1]
	v_fma_f32 v35, v147, s92, -v142
	v_cndmask_b32_e32 v52, v180, v52, vcc
	v_cmp_le_i32_e32 vcc, v171, v136
	v_exp_f32_e32 v34, v34
	s_nop 0
	v_cndmask_b32_e32 v159, v180, v36, vcc
	v_cmp_le_i32_e32 vcc, v186, v136
	v_exp_f32_e32 v36, v35
	v_fma_f32 v35, v51, s92, -v142
	v_cndmask_b32_e32 v53, v180, v53, vcc
	v_cmp_le_i32_e32 vcc, v187, v136
	v_exp_f32_e32 v35, v35
	s_nop 0
	v_cndmask_b32_e32 v217, v180, v37, vcc
	v_cmp_le_i32_e32 vcc, v188, v136
	v_fma_f32 v37, v50, s92, -v142
	v_exp_f32_e32 v37, v37
	v_cndmask_b32_e32 v54, v180, v54, vcc
	v_cmp_le_i32_e32 vcc, v189, v136
	v_pk_mul_f32 v[34:35], v[66:67], v[34:35]
	v_pk_mul_f32 v[36:37], v[66:67], v[36:37]
	v_cndmask_b32_e32 v218, v180, v38, vcc
	v_cmp_le_i32_e32 vcc, v190, v136
	v_fma_f32 v38, v52, s92, -v142
	v_exp_f32_e32 v38, v38
	v_cndmask_b32_e32 v55, v180, v55, vcc
	v_cmp_le_i32_e32 vcc, v191, v136
	s_nop 1
	v_cndmask_b32_e32 v219, v180, v39, vcc
	v_cmp_le_i32_e32 vcc, v192, v136
	v_fma_f32 v39, v159, s92, -v142
	v_add_f32_e32 v159, v34, v35
	v_cndmask_b32_e32 v56, v180, v56, vcc
	v_cmp_le_i32_e32 vcc, v193, v136
	v_cvt_pk_bf16_f32 v34, v34, v35
	s_nop 0
	v_cndmask_b32_e32 v220, v180, v40, vcc
	v_cmp_le_i32_e32 vcc, v194, v136
	v_exp_f32_e32 v40, v39
	v_fma_f32 v39, v53, s92, -v142
	v_cndmask_b32_e32 v57, v180, v57, vcc
	v_cmp_le_i32_e32 vcc, v195, v136
	v_exp_f32_e32 v39, v39
	s_nop 0
	v_cndmask_b32_e32 v221, v180, v41, vcc
	v_cmp_le_i32_e32 vcc, v196, v136
	v_fma_f32 v41, v217, s92, -v142
	v_exp_f32_e32 v41, v41
	v_cndmask_b32_e32 v58, v180, v58, vcc
	v_cmp_le_i32_e32 vcc, v197, v136
	v_fma_f32 v50, v58, s92, -v142
	v_pk_mul_f32 v[38:39], v[66:67], v[38:39]
	v_cndmask_b32_e32 v222, v180, v42, vcc
	v_cmp_le_i32_e32 vcc, v198, v136
	v_fma_f32 v51, v222, s92, -v142
	v_exp_f32_e32 v52, v51
	v_cndmask_b32_e32 v59, v180, v59, vcc
	v_cmp_le_i32_e32 vcc, v199, v136
	v_fma_f32 v51, v59, s92, -v142
	v_fma_f32 v42, v54, s92, -v142
	v_cndmask_b32_e32 v223, v180, v43, vcc
	v_cmp_le_i32_e32 vcc, v200, v136
	v_fma_f32 v43, v218, s92, -v142
	v_exp_f32_e32 v42, v42
	v_cndmask_b32_e32 v60, v180, v60, vcc
	v_cmp_le_i32_e32 vcc, v201, v136
	v_fma_f32 v54, v60, s92, -v142
	v_exp_f32_e32 v54, v54
	v_cndmask_b32_e32 v224, v180, v44, vcc
	v_cmp_le_i32_e32 vcc, v202, v136
	v_exp_f32_e32 v44, v43
	v_fma_f32 v43, v55, s92, -v142
	v_cndmask_b32_e32 v61, v180, v61, vcc
	v_cmp_le_i32_e32 vcc, v203, v136
	v_fma_f32 v55, v224, s92, -v142
	v_exp_f32_e32 v43, v43
	v_cndmask_b32_e32 v225, v180, v45, vcc
	v_cmp_le_i32_e32 vcc, v204, v136
	v_fma_f32 v45, v219, s92, -v142
	v_exp_f32_e32 v45, v45
	v_cndmask_b32_e32 v62, v180, v62, vcc
	v_cmp_le_i32_e32 vcc, v205, v136
	v_fma_f32 v58, v62, s92, -v142
	v_exp_f32_e32 v50, v50
	v_cndmask_b32_e32 v226, v180, v46, vcc
	v_cmp_le_i32_e32 vcc, v206, v136
	v_fma_f32 v46, v56, s92, -v142
	v_fma_f32 v59, v226, s92, -v142
	v_cndmask_b32_e32 v63, v180, v63, vcc
	v_cmp_le_i32_e32 vcc, v207, v136
; DI float ex2(float x) { return __builtin_amdgcn_exp2f(x); }
; DI void nsa_unit(const bf16* PR, const float* AUX, const bf16* KC, const bf16* VC, bf16* MIX, char* sm, int b, int qb) {
;     ...
;         for (int it = 0; it < ntc; ++it) { const char* cb = sm + it * STG;
;               f32x16 x0, x1; qk_tile(cb, qr, r32, hi, x0, x1); bf16x8 vf[8]; v_load(cb + 9216, lane, hi, vf); mask_tile(x0, x1, 0, khc - 64 * it, hi);
; #pragma unroll
;               for (int i = 0; i < 16; ++i) { x0[i] = ex2(fmaf(x0[i], C2, -m)) * invl; x1[i] = ex2(fmaf(x1[i], C2, -m)) * invl; }
;               float qs[8], lastv[8], rcv[8];
; #pragma unroll
;               for (int gq = 0; gq < 4; ++gq) { qs[gq] = (x0[4 * gq] + x0[4 * gq + 1]) + (x0[4 * gq + 2] + x0[4 * gq + 3]); lastv[gq] = x0[4 * gq + 3];
;                                                qs[4 + gq] = (x1[4 * gq] + x1[4 * gq + 1]) + (x1[4 * gq + 2] + x1[4 * gq + 3]); lastv[4 + gq] = x1[4 * gq + 3]; }
; #pragma unroll
;               for (int gq = 0; gq < 8; ++gq) rcv[gq] = __shfl_xor(lastv[gq], 32);
; #pragma unroll
;               for (int gq = 0; gq < 8; ++gq) {
;                   const float add0 = gq > 0 ? rcv[gq - 1] : carry;
;                   const float val = qs[gq] + (hi ? rcv[gq] : add0);
;                   impL[(g * 64 + ql) * 33 + 16 * it + 2 * gq + hi] = val;
;               }
;               carry = rcv[7];
;               pv_tile(vf, x0, x1, o0, o1); }
	v_exp_f32_e32 v46, v46
	v_exp_f32_e32 v60, v59
	v_cndmask_b32_e32 v227, v180, v47, vcc
	v_cmp_le_i32_e32 vcc, v208, v136
	v_fma_f32 v47, v220, s92, -v142
	v_fma_f32 v59, v63, s92, -v142
	v_cndmask_b32_e32 v64, v180, v64, vcc
	v_cmp_le_i32_e32 vcc, v209, v136
	v_exp_f32_e32 v56, v55
	v_fma_f32 v55, v61, s92, -v142
	v_cndmask_b32_e32 v228, v180, v48, vcc
	v_cmp_le_i32_e32 vcc, v210, v136
	v_exp_f32_e32 v48, v47
	v_fma_f32 v47, v57, s92, -v142
	v_cndmask_b32_e32 v65, v180, v65, vcc
	v_exp_f32_e32 v47, v47
	v_fma_f32 v63, v228, s92, -v142
	v_cmp_le_i32_e32 vcc, v211, v136
	v_fma_f32 v62, v64, s92, -v142
	v_exp_f32_e32 v64, v63
	v_fma_f32 v63, v65, s92, -v142
	v_cndmask_b32_e32 v229, v180, v49, vcc
	v_fma_f32 v49, v221, s92, -v142
	v_exp_f32_e32 v55, v55
	v_exp_f32_e32 v62, v62
	v_exp_f32_e32 v63, v63
	v_exp_f32_e32 v49, v49
	v_pk_mul_f32 v[46:47], v[66:67], v[46:47]
	v_exp_f32_e32 v51, v51
	v_fma_f32 v53, v223, s92, -v142
	v_fma_f32 v57, v225, s92, -v142
	ds_bpermute_b32 v230, v212, v39
	v_pk_mul_f32 v[40:41], v[66:67], v[40:41]
	v_exp_f32_e32 v53, v53
	v_exp_f32_e32 v57, v57
	v_fma_f32 v65, v229, s92, -v142
	v_add_f32_e32 v147, v38, v39
	ds_bpermute_b32 v229, v212, v47
	v_pk_mul_f32 v[42:43], v[66:67], v[42:43]
	v_pk_mul_f32 v[54:55], v[66:67], v[54:55]
	v_exp_f32_e32 v58, v58
	v_exp_f32_e32 v59, v59
	v_pk_mul_f32 v[62:63], v[66:67], v[62:63]
	v_add_f32_e32 v218, v159, v147
	v_add_f32_e32 v147, v40, v41
	v_add_f32_e32 v159, v36, v37
	v_pk_mul_f32 v[44:45], v[66:67], v[44:45]
	v_pk_mul_f32 v[48:49], v[66:67], v[48:49]
	v_fma_f32 v61, v227, s92, -v142
	v_add_f32_e32 v159, v159, v147
	v_add_f32_e32 v147, v46, v47
	v_add_f32_e32 v217, v42, v43
	ds_bpermute_b32 v228, v212, v55
	ds_bpermute_b32 v227, v212, v63
	v_pk_mul_f32 v[50:51], v[66:67], v[50:51]
	v_add_f32_e32 v220, v217, v147
	v_add_f32_e32 v147, v48, v49
	v_add_f32_e32 v217, v44, v45
	v_pk_mul_f32 v[52:53], v[66:67], v[52:53]
	v_pk_mul_f32 v[56:57], v[66:67], v[56:57]
	v_add_f32_e32 v217, v217, v147
	v_add_f32_e32 v147, v54, v55
	v_add_f32_e32 v219, v50, v51
	s_waitcnt lgkmcnt(3)
	v_cndmask_b32_e64 v158, v230, v158, s[4:5]
	v_pk_mul_f32 v[58:59], v[66:67], v[58:59]
	v_add_f32_e32 v222, v219, v147
	v_add_f32_e32 v147, v56, v57
	v_add_f32_e32 v219, v52, v53
	v_add_f32_e32 v158, v158, v218
	s_waitcnt lgkmcnt(2)
	v_cndmask_b32_e64 v218, v229, v230, s[4:5]
	v_add_f32_e32 v219, v219, v147
	v_add_f32_e32 v147, v62, v63
	v_add_f32_e32 v221, v58, v59
	v_add_f32_e32 v218, v218, v220
	v_add_f32_e32 v223, v221, v147
	ds_write2_b32 v231, v158, v218 offset1:2
	s_waitcnt lgkmcnt(2)
	v_cndmask_b32_e64 v158, v228, v229, s[4:5]
	s_waitcnt lgkmcnt(1)
	v_cndmask_b32_e64 v218, v227, v228, s[4:5]
	v_add_f32_e32 v158, v158, v222
	v_add_f32_e32 v218, v218, v223
	ds_write2_b32 v231, v158, v218 offset0:4 offset1:6
	v_cvt_pk_bf16_f32 v218, v36, v37
	v_cvt_pk_bf16_f32 v35, v38, v39
	v_cvt_pk_bf16_f32 v36, v42, v43
	v_cvt_pk_bf16_f32 v37, v46, v47
	v_exp_f32_e32 v61, v61
	v_exp_f32_e32 v65, v65
	v_mfma_f32_32x32x16_bf16 v[2:17], v[100:103], v[34:37], v[2:17]
	ds_bpermute_b32 v226, v212, v41
	v_mul_f32_e64 v60, v66, v60
	v_mul_f32_e64 v61, v67, v61
	v_mul_f32_e64 v64, v66, v64
	v_mul_f32_e64 v65, v67, v65
	ds_bpermute_b32 v225, v212, v49
	v_cvt_pk_bf16_f32 v50, v50, v51
	v_cvt_pk_bf16_f32 v222, v52, v53
	v_cvt_pk_bf16_f32 v51, v54, v55
	v_mfma_f32_32x32x16_bf16 v[18:33], v[104:107], v[34:37], v[18:33]
	v_cvt_pk_bf16_f32 v52, v58, v59
	v_cvt_pk_bf16_f32 v53, v62, v63
	v_add_f32_e32 v147, v64, v65
	v_add_f32_e32 v221, v60, v61
	v_add_f32_e32 v221, v221, v147
	ds_bpermute_b32 v224, v212, v57
	ds_bpermute_b32 v147, v212, v65
	v_mfma_f32_32x32x16_bf16 v[2:17], v[108:111], v[50:53], v[2:17]
	s_waitcnt lgkmcnt(3)
	v_cndmask_b32_e64 v158, v226, v227, s[4:5]
	v_add_f32_e32 v158, v158, v159
	s_waitcnt lgkmcnt(2)
	v_cndmask_b32_e64 v159, v225, v226, s[4:5]
	v_add_f32_e32 v159, v159, v217
	ds_write2_b32 v231, v158, v159 offset0:8 offset1:10
	s_waitcnt lgkmcnt(2)
	v_cndmask_b32_e64 v158, v224, v225, s[4:5]
	s_waitcnt lgkmcnt(1)
	v_cndmask_b32_e64 v159, v147, v224, s[4:5]
	v_mfma_f32_32x32x16_bf16 v[18:33], v[112:115], v[50:53], v[18:33]
	v_add_f32_e32 v158, v158, v219
	v_add_f32_e32 v159, v159, v221
	v_cvt_pk_bf16_f32 v219, v40, v41
	v_cvt_pk_bf16_f32 v220, v44, v45
	v_cvt_pk_bf16_f32 v221, v48, v49
	v_cvt_pk_bf16_f32 v223, v56, v57
	v_cvt_pk_bf16_f32 v224, v60, v61
	v_mfma_f32_32x32x16_bf16 v[2:17], v[116:119], v[218:221], v[2:17]
	v_cvt_pk_bf16_f32 v225, v64, v65
	ds_write2_b32 v231, v158, v159 offset0:12 offset1:14
	v_subrev_u32_e32 v136, 64, v136
	v_mov_b32_e32 v158, v147
	v_mfma_f32_32x32x16_bf16 v[18:33], v[120:123], v[218:221], v[18:33]
	v_mfma_f32_32x32x16_bf16 v[2:17], v[124:127], v[222:225], v[2:17]
	v_mfma_f32_32x32x16_bf16 v[18:33], v[128:131], v[222:225], v[18:33]
	s_cbranch_scc0 .LBB0_490
; DI float sigm_f(float z) { return __builtin_amdgcn_rcpf(1.f + ex2(-1.4426950408889634f * z)); }
; DI void nsa_unit(const bf16* PR, const float* AUX, const bf16* KC, const bf16* VC, bf16* MIX, char* sm, int b, int qb) {
;     ...
;     const float g0 = sigm_f(AUX[row * 32 + 6 + 3 * g]), g1 = sigm_f(AUX[row * 32 + 7 + 3 * g]), g2 = sigm_f(AUX[row * 32 + 8 + 3 * g]);
;     ...
;         __syncthreads();
; #pragma unroll
;         for (int i = 0; i < 16; ++i) { tacc[i * 64] = g0 * o0[i]; tacc[(16 + i) * 64] = g0 * o1[i]; }
;     }
;     if (wid == 0) {
;         const unsigned forced = 1u | (1u << cur) | (cur >= 1 ? (1u << (cur - 1)) : 0u);
;         unsigned selbits = forced; const int ncand = cur - 2;
;         if (ncand > 0) {
;             const int nfree = 8 - __popc(forced);
;             if (ncand <= nfree) selbits |= ((1u << (cur - 1)) - 2u);
	v_mul_f32_e32 v0, 0xbfb8aa3b, v138
	v_exp_f32_e32 v0, v0
	s_lshl_b32 s0, s13, 13
	s_add_i32 s16, s0, 0
	s_add_i32 s16, s16, 0x14000
	v_add_f32_e32 v0, 1.0, v0
	v_rcp_f32_e32 v0, v0
	v_lshl_add_u32 v217, v149, 2, s16
	s_waitcnt lgkmcnt(0)
	s_barrier
	v_mul_f32_e32 v2, v0, v2
	v_mul_f32_e32 v3, v0, v3
	v_mul_f32_e32 v18, v0, v18
	ds_write2st64_b32 v217, v2, v3 offset1:1
	v_mul_f32_e32 v2, v0, v19
	ds_write2st64_b32 v217, v18, v2 offset0:16 offset1:17
	v_mul_f32_e32 v2, v0, v4
	v_mul_f32_e32 v4, v0, v5
	v_mul_f32_e32 v3, v0, v20
	ds_write2st64_b32 v217, v2, v4 offset0:2 offset1:3
	v_mul_f32_e32 v2, v0, v21
	ds_write2st64_b32 v217, v3, v2 offset0:18 offset1:19
	v_mul_f32_e32 v2, v0, v6
	v_mul_f32_e32 v4, v0, v7
	v_mul_f32_e32 v3, v0, v22
	ds_write2st64_b32 v217, v2, v4 offset0:4 offset1:5
	v_mul_f32_e32 v2, v0, v23
	ds_write2st64_b32 v217, v3, v2 offset0:20 offset1:21
	v_mul_f32_e32 v2, v0, v8
	v_mul_f32_e32 v4, v0, v9
	v_mul_f32_e32 v3, v0, v24
	ds_write2st64_b32 v217, v2, v4 offset0:6 offset1:7
	v_mul_f32_e32 v2, v0, v25
	ds_write2st64_b32 v217, v3, v2 offset0:22 offset1:23
	v_mul_f32_e32 v2, v0, v10
	v_mul_f32_e32 v4, v0, v11
	v_mul_f32_e32 v3, v0, v26
	ds_write2st64_b32 v217, v2, v4 offset0:8 offset1:9
	v_mul_f32_e32 v2, v0, v27
	ds_write2st64_b32 v217, v3, v2 offset0:24 offset1:25
	v_mul_f32_e32 v2, v0, v12
	v_mul_f32_e32 v4, v0, v13
	v_mul_f32_e32 v3, v0, v28
	ds_write2st64_b32 v217, v2, v4 offset0:10 offset1:11
	v_mul_f32_e32 v2, v0, v29
	ds_write2st64_b32 v217, v3, v2 offset0:26 offset1:27
	v_mul_f32_e32 v2, v0, v14
	v_mul_f32_e32 v4, v0, v15
	v_mul_f32_e32 v3, v0, v30
	ds_write2st64_b32 v217, v2, v4 offset0:12 offset1:13
	v_mul_f32_e32 v2, v0, v31
	ds_write2st64_b32 v217, v3, v2 offset0:28 offset1:29
	v_mul_f32_e32 v2, v0, v16
	v_mul_f32_e32 v3, v0, v32
	v_mul_f32_e32 v4, v0, v17
	v_mul_f32_e32 v0, v0, v33
	s_and_b64 vcc, exec, s[94:95]
	s_mov_b32 s61, s10
	s_mov_b32 s58, 0xda24260
	s_mov_b32 s59, 0x41000000
	s_mov_b32 s60, 0xc3170000
	s_mov_b32 s62, 0xf800000
	ds_write2st64_b32 v217, v2, v4 offset0:14 offset1:15
	ds_write2st64_b32 v217, v3, v0 offset0:30 offset1:31
	s_cbranch_vccz .LBB0_511
	s_sub_i32 s1, 30, s85
	s_lshr_b32 s0, 0x80000000, s85
	s_lshl_b32 s8, 1, s1
	s_cmp_lg_u32 s85, 31
	s_cselect_b32 s1, s8, 0
	s_or_b32 s0, s0, s1
	s_or_b32 s5, s0, 1
	s_cmp_lt_u32 s83, 3
	v_mov_b32_e32 v2, s5
	s_cbranch_scc1 .LBB0_508
	s_bcnt1_i32_b32 s6, s5
	s_sub_i32 s7, 29, s85
	s_sub_i32 s4, 8, s6
	s_cmp_gt_i32 s7, s4
	s_mov_b64 s[0:1], -1
	s_cbranch_scc1 .LBB0_495
	s_add_i32 s8, s8, -2
	s_or_b32 s9, s5, s8
	s_mov_b64 s[0:1], 0

; #define MFMA32(a, b, c) __builtin_amdgcn_mfma_f32_32x32x16_bf16((a), (b), (c), 0, 0, 0)
; DI int nth_set_desc(unsigned m, int n) { for (int i = 0; i < n; ++i) m &= ~(1u << (31 - __clz((int)m))); return 31 - __clz((int)m); }
; DI void qk_tile(const char* kb, const bf16x8 (&qr)[5], int r32, int hi, f32x16& x0, f32x16& x1) {
;     bf16x8 kf[10];
; #pragma unroll
;     for (int d0 = 0; d0 < 4; ++d0) {
;         kf[2 * d0] = *(const bf16x8*)(kb + (2 * d0 + hi) * 1024 + r32 * 16);
;         kf[2 * d0 + 1] = *(const bf16x8*)(kb + (2 * d0 + hi) * 1024 + 512 + r32 * 16);
;     }
;     kf[8] = *(const bf16x8*)(kb + 8192 + r32 * 16);
;     kf[9] = *(const bf16x8*)(kb + 8192 + 512 + r32 * 16);
;     asm volatile("s_waitcnt lgkmcnt(0)" ::: "memory");
; #pragma unroll
;     for (int i = 0; i < 16; ++i) { x0[i] = 0.f; x1[i] = 0.f; }
; #pragma unroll
;     for (int d0 = 0; d0 < 5; ++d0) { x0 = MFMA32(kf[2 * d0], qr[d0], x0); x1 = MFMA32(kf[2 * d0 + 1], qr[d0], x1); }
; }
; DI void nsa_unit(const bf16* PR, const float* AUX, const bf16* KC, const bf16* VC, bf16* MIX, char* sm, int b, int qb) {
;     ...
;         if (it_ >= 0) { const int it = it_; const char* cb = sm + (it & 1) * STG; { const int j = nth_set_desc(anym, it);
;               f32x16 x0, x1; qk_tile(cb, qr, r32, hi, x0, x1); bf16x8 vf[8]; v_load(cb + 9216, lane, hi, vf);
;               const bool selj = ((mysel >> j) & 1u) != 0u;
;               if (j == cur) mask_tile(x0, x1, 0, selj ? t - 64 * j : -1, hi);
.LBB0_520:
	s_bitcmp1_b32 s4, 0
	s_cselect_b32 s1, 0x4800, 0
	s_add_i32 s1, s1, 0
	v_add_u32_e32 v0, s1, v165
	v_add_u32_e32 v2, v0, v166
	ds_read_b128 v[36:39], v2
	ds_read_b128 v[40:43], v2 offset:512
	ds_read_b128 v[100:103], v2 offset:2048
	ds_read_b128 v[104:107], v2 offset:2560
	ds_read_b128 v[108:111], v2 offset:4096
	ds_read_b128 v[112:115], v2 offset:4608
	ds_read_b128 v[116:119], v2 offset:6144
	ds_read_b128 v[120:123], v2 offset:6656
	ds_read_b128 v[124:127], v0 offset:8192
	ds_read_b128 v[128:131], v0 offset:8704
	s_waitcnt lgkmcnt(9)
	v_mfma_f32_32x32x16_bf16 v[52:67], v[36:39], v[68:71], 0
	v_add3_u32 v0, s1, v213, v163
	v_add3_u32 v0, v0, v214, v216
	s_flbit_i32_b32 s0, s0
	s_min_u32 s0, s0, 32
	s_cmp_eq_u32 s85, s0
	s_cselect_b64 s[4:5], -1, 0
	s_waitcnt lgkmcnt(8)
	v_mfma_f32_32x32x16_bf16 v[36:51], v[40:43], v[68:71], 0
	s_cmp_lg_u32 s85, s0
	s_waitcnt lgkmcnt(7)
	v_mfma_f32_32x32x16_bf16 v[52:67], v[100:103], v[72:75], v[52:67]
	s_waitcnt lgkmcnt(6)
	v_mfma_f32_32x32x16_bf16 v[36:51], v[104:107], v[72:75], v[36:51]
	s_waitcnt lgkmcnt(5)
	v_mfma_f32_32x32x16_bf16 v[52:67], v[108:111], v[76:79], v[52:67]
	s_waitcnt lgkmcnt(4)
	v_mfma_f32_32x32x16_bf16 v[36:51], v[112:115], v[76:79], v[36:51]
	s_waitcnt lgkmcnt(3)
	v_mfma_f32_32x32x16_bf16 v[52:67], v[116:119], v[80:83], v[52:67]
	s_waitcnt lgkmcnt(2)
	v_mfma_f32_32x32x16_bf16 v[36:51], v[120:123], v[80:83], v[36:51]
	s_waitcnt lgkmcnt(1)
	v_mfma_f32_32x32x16_bf16 v[52:67], v[124:127], v[96:99], v[52:67]
	s_waitcnt lgkmcnt(0)
	v_mfma_f32_32x32x16_bf16 v[36:51], v[128:131], v[96:99], v[36:51]
	ds_read_b64_tr_b16 v[128:129], v0 offset:9216
	ds_read_b64_tr_b16 v[130:131], v0 offset:9728
	ds_read_b64_tr_b16 v[124:125], v0 offset:13312
	ds_read_b64_tr_b16 v[126:127], v0 offset:13824
	ds_read_b64_tr_b16 v[116:117], v0 offset:10240
	ds_read_b64_tr_b16 v[118:119], v0 offset:10752
	ds_read_b64_tr_b16 v[120:121], v0 offset:14336
	ds_read_b64_tr_b16 v[122:123], v0 offset:14848
	ds_read_b64_tr_b16 v[112:113], v0 offset:11264
	ds_read_b64_tr_b16 v[114:115], v0 offset:11776
	ds_read_b64_tr_b16 v[108:109], v0 offset:15360
	ds_read_b64_tr_b16 v[110:111], v0 offset:15872
	ds_read_b64_tr_b16 v[100:101], v0 offset:12288
	ds_read_b64_tr_b16 v[102:103], v0 offset:12800
	ds_read_b64_tr_b16 v[104:105], v0 offset:16384
	ds_read_b64_tr_b16 v[106:107], v0 offset:16896
	v_lshlrev_b32_e32 v0, s0, v138
	v_and_b32_e32 v0, 0x80000000, v0
	v_cmp_ne_u32_e32 vcc, 0, v0
	s_cbranch_scc1 .LBB0_522
	s_nop 0
	v_cndmask_b32_e32 v0, -1, v133, vcc
	v_cmp_le_i32_e64 s[0:1], v168, v0
	s_nop 1
	v_cndmask_b32_e64 v36, v180, v36, s[0:1]
	v_cmp_lt_i32_e64 s[0:1], v167, v0
	s_nop 1
	v_cndmask_b32_e64 v53, v180, v53, s[0:1]
	v_cmp_le_i32_e64 s[0:1], v167, v0
	s_nop 1
	v_cndmask_b32_e64 v52, v180, v52, s[0:1]
	v_cmp_le_i32_e64 s[0:1], v169, v0
	s_nop 1
	v_cndmask_b32_e64 v37, v180, v37, s[0:1]
	v_cmp_le_i32_e64 s[0:1], v170, v0
	s_nop 1
	v_cndmask_b32_e64 v54, v180, v54, s[0:1]
	v_cmp_le_i32_e64 s[0:1], v171, v0
	s_nop 1
	v_cndmask_b32_e64 v38, v180, v38, s[0:1]
	v_cmp_le_i32_e64 s[0:1], v186, v0
	s_nop 1
	v_cndmask_b32_e64 v55, v180, v55, s[0:1]
	v_cmp_le_i32_e64 s[0:1], v187, v0
	s_nop 1
	v_cndmask_b32_e64 v39, v180, v39, s[0:1]
	v_cmp_le_i32_e64 s[0:1], v188, v0
	s_nop 1
	v_cndmask_b32_e64 v56, v180, v56, s[0:1]
	v_cmp_le_i32_e64 s[0:1], v189, v0
	s_nop 1
	v_cndmask_b32_e64 v40, v180, v40, s[0:1]
	v_cmp_le_i32_e64 s[0:1], v190, v0
	s_nop 1
	v_cndmask_b32_e64 v57, v180, v57, s[0:1]
	v_cmp_le_i32_e64 s[0:1], v191, v0
	s_nop 1
	v_cndmask_b32_e64 v41, v180, v41, s[0:1]
	v_cmp_le_i32_e64 s[0:1], v192, v0
	s_nop 1
	v_cndmask_b32_e64 v58, v180, v58, s[0:1]
	v_cmp_le_i32_e64 s[0:1], v193, v0
	s_nop 1
	v_cndmask_b32_e64 v42, v180, v42, s[0:1]
	v_cmp_le_i32_e64 s[0:1], v194, v0
	s_nop 1
	v_cndmask_b32_e64 v59, v180, v59, s[0:1]
	v_cmp_le_i32_e64 s[0:1], v195, v0
	s_nop 1
	v_cndmask_b32_e64 v43, v180, v43, s[0:1]
	v_cmp_le_i32_e64 s[0:1], v196, v0
	s_nop 1
	v_cndmask_b32_e64 v60, v180, v60, s[0:1]
	v_cmp_le_i32_e64 s[0:1], v197, v0
	s_nop 1
	v_cndmask_b32_e64 v44, v180, v44, s[0:1]
	v_cmp_le_i32_e64 s[0:1], v198, v0
	s_nop 1
	v_cndmask_b32_e64 v61, v180, v61, s[0:1]
	v_cmp_le_i32_e64 s[0:1], v199, v0
	s_nop 1
	v_cndmask_b32_e64 v45, v180, v45, s[0:1]
	v_cmp_le_i32_e64 s[0:1], v200, v0
	s_nop 1
	v_cndmask_b32_e64 v62, v180, v62, s[0:1]
	v_cmp_le_i32_e64 s[0:1], v201, v0
	s_nop 1
	v_cndmask_b32_e64 v46, v180, v46, s[0:1]
	v_cmp_le_i32_e64 s[0:1], v202, v0
	s_nop 1
	v_cndmask_b32_e64 v63, v180, v63, s[0:1]
	v_cmp_le_i32_e64 s[0:1], v203, v0
	s_nop 1
	v_cndmask_b32_e64 v47, v180, v47, s[0:1]
	v_cmp_le_i32_e64 s[0:1], v204, v0
	s_nop 1
	v_cndmask_b32_e64 v64, v180, v64, s[0:1]
	v_cmp_le_i32_e64 s[0:1], v205, v0
	s_nop 1
	v_cndmask_b32_e64 v48, v180, v48, s[0:1]
	v_cmp_le_i32_e64 s[0:1], v206, v0
	s_nop 1
	v_cndmask_b32_e64 v65, v180, v65, s[0:1]
	v_cmp_le_i32_e64 s[0:1], v207, v0
	s_nop 1
	v_cndmask_b32_e64 v49, v180, v49, s[0:1]
	v_cmp_le_i32_e64 s[0:1], v208, v0
	s_nop 1
	v_cndmask_b32_e64 v66, v180, v66, s[0:1]
	v_cmp_le_i32_e64 s[0:1], v209, v0
	s_nop 1
	v_cndmask_b32_e64 v50, v180, v50, s[0:1]
	v_cmp_le_i32_e64 s[0:1], v210, v0
	s_nop 1
	v_cndmask_b32_e64 v67, v180, v67, s[0:1]
	v_cmp_le_i32_e64 s[0:1], v211, v0
	s_nop 1
	v_cndmask_b32_e64 v51, v180, v51, s[0:1]

; #define MFMA32(a, b, c) __builtin_amdgcn_mfma_f32_32x32x16_bf16((a), (b), (c), 0, 0, 0)
; DI void qk_tile(const char* kb, const bf16x8 (&qr)[5], int r32, int hi, f32x16& x0, f32x16& x1) {
;     bf16x8 kf[10];
; #pragma unroll
;     for (int d0 = 0; d0 < 4; ++d0) {
;         kf[2 * d0] = *(const bf16x8*)(kb + (2 * d0 + hi) * 1024 + r32 * 16);
;         kf[2 * d0 + 1] = *(const bf16x8*)(kb + (2 * d0 + hi) * 1024 + 512 + r32 * 16);
;     }
;     kf[8] = *(const bf16x8*)(kb + 8192 + r32 * 16);
;     kf[9] = *(const bf16x8*)(kb + 8192 + 512 + r32 * 16);
;     asm volatile("s_waitcnt lgkmcnt(0)" ::: "memory");
; #pragma unroll
;     for (int i = 0; i < 16; ++i) { x0[i] = 0.f; x1[i] = 0.f; }
; #pragma unroll
;     for (int d0 = 0; d0 < 5; ++d0) { x0 = MFMA32(kf[2 * d0], qr[d0], x0); x1 = MFMA32(kf[2 * d0 + 1], qr[d0], x1); }
; }
; DI void nsa_unit(const bf16* PR, const float* AUX, const bf16* KC, const bf16* VC, bf16* MIX, char* sm, int b, int qb) {
;     ...
;         if (it_ >= 0) { const int it = it_; const char* cb = sm + (it & 1) * STG; { const int j = cur - it;
;               f32x16 x0, x1; qk_tile(cb, qr, r32, hi, x0, x1); bf16x8 vf[8]; v_load(cb + 9216, lane, hi, vf);
;               if (j == cur || j == cur - 8) mask_tile(x0, x1, t - 511 - 64 * j, t - 64 * j, hi);
.LBB0_537:
	s_bitcmp1_b32 s18, 0
	s_cselect_b32 s0, 0x4800, 0
	s_add_i32 s0, s0, 0
	v_add_u32_e32 v0, s0, v165
	v_add_u32_e32 v2, v0, v166
	ds_read_b128 v[36:39], v2
	s_waitcnt vmcnt(2)
	ds_read_b128 v[40:43], v2 offset:512
	ds_read_b128 v[108:111], v2 offset:2048
	ds_read_b128 v[112:115], v2 offset:2560
	ds_read_b128 v[116:119], v2 offset:4096
	ds_read_b128 v[120:123], v2 offset:4608
	ds_read_b128 v[124:127], v2 offset:6144
	ds_read_b128 v[128:131], v2 offset:6656
	ds_read_b128 v[132:135], v0 offset:8192
	ds_read_b128 v[136:139], v0 offset:8704
	s_waitcnt lgkmcnt(9)
	v_mfma_f32_32x32x16_bf16 v[52:67], v[36:39], v[68:71], 0
	v_add3_u32 v0, s0, v213, v163
	v_add3_u32 v0, v0, v214, v216
	s_cmp_eq_u32 s17, -8
	s_cselect_b64 s[0:1], -1, 0
	s_cmp_eq_u32 s17, 0
	s_cselect_b64 s[18:19], -1, 0
	s_waitcnt lgkmcnt(8)
	v_mfma_f32_32x32x16_bf16 v[36:51], v[40:43], v[68:71], 0
	s_or_b64 s[0:1], s[0:1], s[18:19]
	s_andn2_b64 vcc, exec, s[0:1]
	s_waitcnt lgkmcnt(7)
	v_mfma_f32_32x32x16_bf16 v[52:67], v[108:111], v[72:75], v[52:67]
	s_waitcnt lgkmcnt(6)
	v_mfma_f32_32x32x16_bf16 v[36:51], v[112:115], v[72:75], v[36:51]
	s_waitcnt lgkmcnt(5)
	v_mfma_f32_32x32x16_bf16 v[52:67], v[116:119], v[76:79], v[52:67]
	s_waitcnt lgkmcnt(4)
	v_mfma_f32_32x32x16_bf16 v[36:51], v[120:123], v[76:79], v[36:51]
	s_waitcnt lgkmcnt(3)
	v_mfma_f32_32x32x16_bf16 v[52:67], v[124:127], v[80:83], v[52:67]
	s_waitcnt lgkmcnt(2)
	v_mfma_f32_32x32x16_bf16 v[36:51], v[128:131], v[80:83], v[36:51]
	s_waitcnt lgkmcnt(1)
	v_mfma_f32_32x32x16_bf16 v[52:67], v[132:135], v[96:99], v[52:67]
	s_waitcnt lgkmcnt(0)
	v_mfma_f32_32x32x16_bf16 v[36:51], v[136:139], v[96:99], v[36:51]
	ds_read_b64_tr_b16 v[136:137], v0 offset:9216
	ds_read_b64_tr_b16 v[138:139], v0 offset:9728
	ds_read_b64_tr_b16 v[132:133], v0 offset:13312
	ds_read_b64_tr_b16 v[134:135], v0 offset:13824
	ds_read_b64_tr_b16 v[124:125], v0 offset:10240
	ds_read_b64_tr_b16 v[126:127], v0 offset:10752
	ds_read_b64_tr_b16 v[128:129], v0 offset:14336
	ds_read_b64_tr_b16 v[130:131], v0 offset:14848
	ds_read_b64_tr_b16 v[120:121], v0 offset:11264
	ds_read_b64_tr_b16 v[122:123], v0 offset:11776
	ds_read_b64_tr_b16 v[116:117], v0 offset:15360
	ds_read_b64_tr_b16 v[118:119], v0 offset:15872
	ds_read_b64_tr_b16 v[108:109], v0 offset:12288
	ds_read_b64_tr_b16 v[110:111], v0 offset:12800
	ds_read_b64_tr_b16 v[112:113], v0 offset:16384
	ds_read_b64_tr_b16 v[114:115], v0 offset:16896
	s_cbranch_vccnz .LBB0_539
	v_add_u32_e32 v0, 0x1ff, v222
	v_cmp_lt_i32_e32 vcc, v167, v222
	v_cmp_gt_i32_e64 s[0:1], v167, v0
	s_or_b64 vcc, vcc, s[0:1]
	v_cndmask_b32_e32 v52, v52, v180, vcc
	v_cmp_lt_i32_e32 vcc, v168, v222
	v_cmp_gt_i32_e64 s[0:1], v168, v0
	s_or_b64 vcc, vcc, s[0:1]
	v_cndmask_b32_e32 v36, v36, v180, vcc
	v_cmp_lt_i32_e32 vcc, v221, v222
	v_cmp_ge_i32_e64 s[0:1], v167, v0
	s_or_b64 vcc, vcc, s[0:1]
	v_cndmask_b32_e32 v53, v53, v180, vcc
	v_cmp_lt_i32_e32 vcc, v169, v222
	v_cmp_gt_i32_e64 s[0:1], v169, v0
	s_or_b64 vcc, vcc, s[0:1]
	v_cndmask_b32_e32 v37, v37, v180, vcc
	v_cmp_lt_i32_e32 vcc, v170, v222
	v_cmp_gt_i32_e64 s[0:1], v170, v0
	s_or_b64 vcc, vcc, s[0:1]
	v_cndmask_b32_e32 v54, v54, v180, vcc
	v_cmp_lt_i32_e32 vcc, v171, v222
	v_cmp_gt_i32_e64 s[0:1], v171, v0
	s_or_b64 vcc, vcc, s[0:1]
	v_cndmask_b32_e32 v38, v38, v180, vcc
	v_cmp_lt_i32_e32 vcc, v186, v222
	v_cmp_gt_i32_e64 s[0:1], v186, v0
	s_or_b64 vcc, vcc, s[0:1]
	v_cndmask_b32_e32 v55, v55, v180, vcc
	v_cmp_lt_i32_e32 vcc, v187, v222
	v_cmp_gt_i32_e64 s[0:1], v187, v0
	s_or_b64 vcc, vcc, s[0:1]
	v_cndmask_b32_e32 v39, v39, v180, vcc
	v_cmp_lt_i32_e32 vcc, v188, v222
	v_cmp_gt_i32_e64 s[0:1], v188, v0
	s_or_b64 vcc, vcc, s[0:1]
	v_cndmask_b32_e32 v56, v56, v180, vcc
	v_cmp_lt_i32_e32 vcc, v189, v222
	v_cmp_gt_i32_e64 s[0:1], v189, v0
	s_or_b64 vcc, vcc, s[0:1]
	v_cndmask_b32_e32 v40, v40, v180, vcc
	v_cmp_lt_i32_e32 vcc, v190, v222
	v_cmp_gt_i32_e64 s[0:1], v190, v0
	s_or_b64 vcc, vcc, s[0:1]
	v_cndmask_b32_e32 v57, v57, v180, vcc
	v_cmp_lt_i32_e32 vcc, v191, v222
	v_cmp_gt_i32_e64 s[0:1], v191, v0
	s_or_b64 vcc, vcc, s[0:1]
	v_cndmask_b32_e32 v41, v41, v180, vcc
	v_cmp_lt_i32_e32 vcc, v192, v222
	v_cmp_gt_i32_e64 s[0:1], v192, v0
	s_or_b64 vcc, vcc, s[0:1]
	v_cndmask_b32_e32 v58, v58, v180, vcc
	v_cmp_lt_i32_e32 vcc, v193, v222
	v_cmp_gt_i32_e64 s[0:1], v193, v0
	s_or_b64 vcc, vcc, s[0:1]
	v_cndmask_b32_e32 v42, v42, v180, vcc
	v_cmp_lt_i32_e32 vcc, v194, v222
	v_cmp_gt_i32_e64 s[0:1], v194, v0
	s_or_b64 vcc, vcc, s[0:1]
	v_cndmask_b32_e32 v59, v59, v180, vcc
	v_cmp_lt_i32_e32 vcc, v195, v222
	v_cmp_gt_i32_e64 s[0:1], v195, v0
	s_or_b64 vcc, vcc, s[0:1]
	v_cndmask_b32_e32 v43, v43, v180, vcc
	v_cmp_lt_i32_e32 vcc, v196, v222
	v_cmp_gt_i32_e64 s[0:1], v196, v0
	s_or_b64 vcc, vcc, s[0:1]
	v_cndmask_b32_e32 v60, v60, v180, vcc
	v_cmp_lt_i32_e32 vcc, v197, v222
	v_cmp_gt_i32_e64 s[0:1], v197, v0
	s_or_b64 vcc, vcc, s[0:1]
	v_cndmask_b32_e32 v44, v44, v180, vcc
	v_cmp_lt_i32_e32 vcc, v198, v222
	v_cmp_gt_i32_e64 s[0:1], v198, v0
	s_or_b64 vcc, vcc, s[0:1]
	v_cndmask_b32_e32 v61, v61, v180, vcc
	v_cmp_lt_i32_e32 vcc, v199, v222
	v_cmp_gt_i32_e64 s[0:1], v199, v0
	s_or_b64 vcc, vcc, s[0:1]
	v_cndmask_b32_e32 v45, v45, v180, vcc
	v_cmp_lt_i32_e32 vcc, v200, v222
	v_cmp_gt_i32_e64 s[0:1], v200, v0
	s_or_b64 vcc, vcc, s[0:1]
	v_cndmask_b32_e32 v62, v62, v180, vcc
	v_cmp_lt_i32_e32 vcc, v201, v222
	v_cmp_gt_i32_e64 s[0:1], v201, v0
	s_or_b64 vcc, vcc, s[0:1]
	v_cndmask_b32_e32 v46, v46, v180, vcc
	v_cmp_lt_i32_e32 vcc, v202, v222
	v_cmp_gt_i32_e64 s[0:1], v202, v0
	s_or_b64 vcc, vcc, s[0:1]
	v_cndmask_b32_e32 v63, v63, v180, vcc
	v_cmp_lt_i32_e32 vcc, v203, v222
	v_cmp_gt_i32_e64 s[0:1], v203, v0
	s_or_b64 vcc, vcc, s[0:1]
	v_cndmask_b32_e32 v47, v47, v180, vcc
	v_cmp_lt_i32_e32 vcc, v204, v222
	v_cmp_gt_i32_e64 s[0:1], v204, v0
	s_or_b64 vcc, vcc, s[0:1]
	v_cndmask_b32_e32 v64, v64, v180, vcc
	v_cmp_lt_i32_e32 vcc, v205, v222
	v_cmp_gt_i32_e64 s[0:1], v205, v0
	s_or_b64 vcc, vcc, s[0:1]
	v_cndmask_b32_e32 v48, v48, v180, vcc
	v_cmp_lt_i32_e32 vcc, v206, v222
	v_cmp_gt_i32_e64 s[0:1], v206, v0
	s_or_b64 vcc, vcc, s[0:1]
	v_cndmask_b32_e32 v65, v65, v180, vcc
	v_cmp_lt_i32_e32 vcc, v207, v222
	v_cmp_gt_i32_e64 s[0:1], v207, v0
	s_or_b64 vcc, vcc, s[0:1]
	v_cndmask_b32_e32 v49, v49, v180, vcc
	v_cmp_lt_i32_e32 vcc, v208, v222
	v_cmp_gt_i32_e64 s[0:1], v208, v0
	s_or_b64 vcc, vcc, s[0:1]
	v_cndmask_b32_e32 v66, v66, v180, vcc
	v_cmp_lt_i32_e32 vcc, v209, v222
	v_cmp_gt_i32_e64 s[0:1], v209, v0
	s_or_b64 vcc, vcc, s[0:1]
	v_cndmask_b32_e32 v50, v50, v180, vcc
	v_cmp_lt_i32_e32 vcc, v210, v222
	v_cmp_gt_i32_e64 s[0:1], v210, v0
	s_or_b64 vcc, vcc, s[0:1]
	v_cndmask_b32_e32 v67, v67, v180, vcc
	v_cmp_lt_i32_e32 vcc, v211, v222
	v_cmp_gt_i32_e64 s[0:1], v211, v0
	s_or_b64 vcc, vcc, s[0:1]
	v_cndmask_b32_e32 v51, v51, v180, vcc
